# GEMM phases: accumulator zeroing (128 v_mov per tile) removed; first K-iteration peeled with C=0 on first MFMA per accumulator
# speedup vs baseline: 1.0025x; 1.0025x over previous
; template <class Epi, class Sched, bool ALIGN_EPI = false, bool SP2 = false>
; __device__ __forceinline__ void gemm_phase(PG8_LAS unsigned char* lds, const Gemm g, const Sched& S, const Epi& E) {
;     ...
;         const bool has_next = S.next(ui + 1, nxt);
;         const char* nA = has_next ? (const char*)g.A + (size_t)nxt.pm * tstep : cA; const char* nB = has_next ? (const char*)g.Bt + (size_t)nxt.pn * tstep : cB;
;         for (int t = 0; t < nt; t += 2) {
;             const bool last = (t == nt - 2);
;             const char* a1 = cA + (size_t)(t + 1) * kstep;
;             const char* a2 = last ? nA : cA + (size_t)(t + 2) * kstep; const char* b2 = last ? nB : cB + (size_t)(t + 2) * kstep;
;             const char* a3 = a2 + kstep; const char* b3 = b2 + kstep;
;     ...
; #pragma unroll
;         for (int a = 0; a < 2; ++a)
; #pragma unroll
;             for (int b = 0; b < 2; ++b)
; #pragma unroll
;                 for (int m = 0; m < 4; ++m)
; #pragma unroll
;                     for (int n = 0; n < 2; ++n) acc[a][b][m][n] = (f32x4){0.f, 0.f, 0.f, 0.f};
.LBB0_15:
	s_ashr_i32 s25, s24, 31
	s_lshl_b64 s[26:27], s[24:25], 20
	s_add_u32 s26, s40, s26
	s_addc_u32 s27, s41, s27
	s_and_b64 s[28:29], s[4:5], exec
	s_cselect_b32 s25, s27, s35
	s_cselect_b32 s65, s26, s34
	s_ashr_i32 s23, s22, 31
	s_lshl_b64 s[28:29], s[22:23], 20
	s_add_u32 s28, s42, s28
	s_addc_u32 s29, s43, s29
	s_and_b64 s[38:39], s[4:5], exec
	s_cselect_b32 s23, s29, s37
	s_cselect_b32 s66, s28, s36
	s_add_u32 s34, s34, 0x80080
	s_addc_u32 s35, s35, 0
	s_add_u32 s67, s36, 0x100

; template <class Epi, class Sched, bool ALIGN_EPI = false, bool SP2 = false>
; __device__ __forceinline__ void gemm_phase(PG8_LAS unsigned char* lds, const Gemm g, const Sched& S, const Epi& E) {
;     ...
; #pragma unroll
;         for (int a = 0; a < 2; ++a)
; #pragma unroll
;             for (int b = 0; b < 2; ++b)
; #pragma unroll
;                 for (int m = 0; m < 4; ++m)
; #pragma unroll
;                     for (int n = 0; n < 2; ++n) acc[a][b][m][n] = (f32x4){0.f, 0.f, 0.f, 0.f};
	s_addc_u32 s68, s37, 0
	s_mov_b32 s69, -2


; #define PG8_STAGE(bufoff, gbase, voff) do { _Pragma("unroll") for (int _i = 0; _i < 2; ++_i) \
;         __builtin_amdgcn_global_load_lds((const unsigned*)((const char*)(gbase) + (voff)[_i]), (PG8_LAS unsigned*)(lds + (bufoff) + ldsw + _i * 8192), 16, 0, 0); } while (0)
; #define PG8_LDA(dst, b, h) do { _Pragma("unroll") for (int m = 0; m < 4; ++m) _Pragma("unroll") for (int k = 0; k < 2; ++k) dst[m][k] = *(const PG8_LAS bf16x8*)(lds + PG8_SA(b, h) + aoff + m * 2048 + k * 1024); } while (0)
; #define PG8_LDB(dst, b, h) do { _Pragma("unroll") for (int n = 0; n < 2; ++n) _Pragma("unroll") for (int k = 0; k < 2; ++k) dst[n][k] = *(const PG8_LAS bf16x8*)(lds + PG8_SB(b, h) + boff + n * 2048 + k * 1024); } while (0)
; #define PG8_MMA(ai, bj, At, Bt) do { __builtin_amdgcn_s_setprio(1); _Pragma("unroll") for (int m = 0; m < 4; ++m) _Pragma("unroll") for (int n = 0; n < 2; ++n) _Pragma("unroll") for (int k = 0; k < 2; ++k) \
;         acc[ai][bj][m][n] = __builtin_amdgcn_mfma_f32_16x16x32_bf16(Bt[n][k], At[m][k], acc[ai][bj][m][n], 0, 0, 0); __builtin_amdgcn_s_setprio(0); } while (0)
; #define PG8_WAIT_V(n) asm volatile("s_waitcnt vmcnt(" #n ")" ::: "memory")
; #define PG8_WAIT_L(n) asm volatile("s_waitcnt lgkmcnt(" #n ")" ::: "memory")
; template <class Epi, class Sched, bool ALIGN_EPI = false, bool SP2 = false>
; __device__ __forceinline__ void gemm_phase(PG8_LAS unsigned char* lds, const Gemm g, const Sched& S, const Epi& E) {
;     ...
;             const bool last = (t == nt - 2);
;             const char* a1 = cA + (size_t)(t + 1) * kstep;
;             const char* a2 = last ? nA : cA + (size_t)(t + 2) * kstep; const char* b2 = last ? nB : cB + (size_t)(t + 2) * kstep;
;             const char* a3 = a2 + kstep; const char* b3 = b2 + kstep;
;             if (last && has_next) S.a_ready(nxt);
;             if constexpr (SP2) {
;             PG8_LDB(B0, 0, 0); PG8_LDB(B1, 0, 1); PG8_SCHED; PG8_LDA(At, 0, 0); PG8_STAGE(PG8_SA(1, 1), a1 + hstep, voffA);
;             PG8_WAIT_V(8); PG8_WAIT_L(0); PG8_BAR; PG8_MMA(0, 0, At, B0); PG8_MMA(0, 1, At, B1); PG8_BAR; PG8_SCHED;
;             PG8_LDA(At, 0, 1); PG8_STAGE(PG8_SB(0, 0), b2, voffB); PG8_STAGE(PG8_SB(0, 1), b2 + hstep, voffB); PG8_STAGE(PG8_SA(0, 0), a2, voffA);
;             PG8_WAIT_V(8); PG8_WAIT_L(0); PG8_BAR; PG8_MMA(1, 0, At, B0); PG8_MMA(1, 1, At, B1); PG8_BAR; PG8_SCHED;
	ds_read_b128 v[154:157], v150
	ds_read_b128 v[158:161], v150 offset:1024
	ds_read_b128 v[162:165], v150 offset:2048
	ds_read_b128 v[166:169], v150 offset:3072
	ds_read_b128 v[170:173], v151
	ds_read_b128 v[174:177], v151 offset:1024
	ds_read_b128 v[178:181], v151 offset:2048
	ds_read_b128 v[182:185], v151 offset:3072
	s_add_u32 s36, s34, 0xfff80080
	s_addc_u32 s37, s35, -1
	s_cmp_eq_u32 s69, 28
	s_cselect_b32 s39, s25, s37
	s_cselect_b32 s38, s65, s36
	s_cselect_b32 s37, s23, s68
	s_cselect_b32 s36, s66, s67
	v_lshl_add_u64 v[146:147], s[34:35], 0, v[136:137]
	s_add_i32 m0, s31, 0xc000
	ds_read_b128 v[186:189], v152
	ds_read_b128 v[190:193], v152 offset:1024
	ds_read_b128 v[194:197], v152 offset:2048
	ds_read_b128 v[198:201], v152 offset:3072
	ds_read_b128 v[202:205], v152 offset:4096
	ds_read_b128 v[210:213], v152 offset:5120
	ds_read_b128 v[214:217], v152 offset:6144
	ds_read_b128 v[218:221], v152 offset:7168
	global_load_lds_dwordx4 v[146:147], off
	v_lshl_add_u64 v[146:147], s[34:35], 0, v[138:139]
	s_add_i32 m0, s31, 0xe000
	s_nop 0
	global_load_lds_dwordx4 v[146:147], off
	s_waitcnt vmcnt(8)
	s_waitcnt lgkmcnt(0)
	s_barrier
	s_setprio 1
	s_waitcnt lgkmcnt(0)
	v_mfma_f32_16x16x32_bf16 v[124:127], v[154:157], v[186:189], 0
	v_mfma_f32_16x16x32_bf16 v[120:123], v[162:165], v[186:189], 0
	v_mfma_f32_16x16x32_bf16 v[116:119], v[154:157], v[194:197], 0
	v_mfma_f32_16x16x32_bf16 v[112:115], v[162:165], v[194:197], 0
	v_mfma_f32_16x16x32_bf16 v[100:103], v[154:157], v[202:205], 0
	v_mfma_f32_16x16x32_bf16 v[96:99], v[162:165], v[202:205], 0
	v_mfma_f32_16x16x32_bf16 v[80:83], v[154:157], v[214:217], 0
	v_mfma_f32_16x16x32_bf16 v[76:79], v[162:165], v[214:217], 0
	v_mfma_f32_16x16x32_bf16 v[124:127], v[158:161], v[190:193], v[124:127]
	v_mfma_f32_16x16x32_bf16 v[120:123], v[166:169], v[190:193], v[120:123]
	v_mfma_f32_16x16x32_bf16 v[116:119], v[158:161], v[198:201], v[116:119]
	v_mfma_f32_16x16x32_bf16 v[112:115], v[166:169], v[198:201], v[112:115]
	v_mfma_f32_16x16x32_bf16 v[100:103], v[158:161], v[210:213], v[100:103]
	v_mfma_f32_16x16x32_bf16 v[96:99], v[166:169], v[210:213], v[96:99]
	v_mfma_f32_16x16x32_bf16 v[80:83], v[158:161], v[218:221], v[80:83]
	v_mfma_f32_16x16x32_bf16 v[76:79], v[166:169], v[218:221], v[76:79]
	s_setprio 0
	s_setprio 1
	v_mfma_f32_16x16x32_bf16 v[108:111], v[170:173], v[186:189], 0
	v_mfma_f32_16x16x32_bf16 v[104:107], v[178:181], v[186:189], 0
	v_mfma_f32_16x16x32_bf16 v[92:95], v[170:173], v[194:197], 0
	v_mfma_f32_16x16x32_bf16 v[88:91], v[178:181], v[194:197], 0
	v_mfma_f32_16x16x32_bf16 v[84:87], v[170:173], v[202:205], 0
	v_mfma_f32_16x16x32_bf16 v[72:75], v[178:181], v[202:205], 0
	v_mfma_f32_16x16x32_bf16 v[68:71], v[170:173], v[214:217], 0
	v_mfma_f32_16x16x32_bf16 v[64:67], v[178:181], v[214:217], 0
	v_mfma_f32_16x16x32_bf16 v[108:111], v[174:177], v[190:193], v[108:111]
	v_mfma_f32_16x16x32_bf16 v[104:107], v[182:185], v[190:193], v[104:107]
	v_mfma_f32_16x16x32_bf16 v[92:95], v[174:177], v[198:201], v[92:95]
	v_mfma_f32_16x16x32_bf16 v[88:91], v[182:185], v[198:201], v[88:91]
	v_mfma_f32_16x16x32_bf16 v[84:87], v[174:177], v[210:213], v[84:87]
	v_mfma_f32_16x16x32_bf16 v[72:75], v[182:185], v[210:213], v[72:75]
	v_mfma_f32_16x16x32_bf16 v[68:71], v[174:177], v[218:221], v[68:71]
	v_mfma_f32_16x16x32_bf16 v[64:67], v[182:185], v[218:221], v[64:67]
	s_setprio 0
	s_barrier
	s_add_i32 s70, s58, s44
	v_lshl_add_u64 v[146:147], s[36:37], 0, v[132:133]
	s_mov_b32 m0, s70
	ds_read_b128 v[186:189], v152 offset:16384
	ds_read_b128 v[190:193], v152 offset:17408
	ds_read_b128 v[194:197], v152 offset:18432
	ds_read_b128 v[198:201], v152 offset:19456
	ds_read_b128 v[202:205], v152 offset:20480
	ds_read_b128 v[210:213], v152 offset:21504
	ds_read_b128 v[214:217], v152 offset:22528
	ds_read_b128 v[218:221], v152 offset:23552
	global_load_lds_dwordx4 v[146:147], off
	s_add_i32 m0, s70, 0x2000
	s_add_u32 s70, s36, 0x80000
	v_lshl_add_u64 v[206:207], s[36:37], 0, v[128:129]
	s_addc_u32 s71, s37, 0
	s_add_i32 s72, s59, s44
	global_load_lds_dwordx4 v[206:207], off
	v_lshl_add_u64 v[222:223], s[70:71], 0, v[132:133]
	s_mov_b32 m0, s72
	v_lshl_add_u64 v[224:225], s[38:39], 0, v[130:131]
	global_load_lds_dwordx4 v[222:223], off
	v_lshl_add_u64 v[222:223], s[70:71], 0, v[128:129]
	s_add_i32 m0, s72, 0x2000
	s_nop 0
	global_load_lds_dwordx4 v[222:223], off
	v_lshl_add_u64 v[222:223], s[38:39], 0, v[134:135]
	s_mov_b32 m0, s31
	s_nop 0
	global_load_lds_dwordx4 v[222:223], off
	s_mov_b32 m0, s47
	s_nop 0
	global_load_lds_dwordx4 v[224:225], off
	s_waitcnt vmcnt(8)
	s_waitcnt lgkmcnt(0)
	s_barrier
; #define PG8_STAGE(bufoff, gbase, voff) do { _Pragma("unroll") for (int _i = 0; _i < 2; ++_i) \
;         __builtin_amdgcn_global_load_lds((const unsigned*)((const char*)(gbase) + (voff)[_i]), (PG8_LAS unsigned*)(lds + (bufoff) + ldsw + _i * 8192), 16, 0, 0); } while (0)
; #define PG8_LDA(dst, b, h) do { _Pragma("unroll") for (int m = 0; m < 4; ++m) _Pragma("unroll") for (int k = 0; k < 2; ++k) dst[m][k] = *(const PG8_LAS bf16x8*)(lds + PG8_SA(b, h) + aoff + m * 2048 + k * 1024); } while (0)
; #define PG8_LDB(dst, b, h) do { _Pragma("unroll") for (int n = 0; n < 2; ++n) _Pragma("unroll") for (int k = 0; k < 2; ++k) dst[n][k] = *(const PG8_LAS bf16x8*)(lds + PG8_SB(b, h) + boff + n * 2048 + k * 1024); } while (0)
; #define PG8_MMA(ai, bj, At, Bt) do { __builtin_amdgcn_s_setprio(1); _Pragma("unroll") for (int m = 0; m < 4; ++m) _Pragma("unroll") for (int n = 0; n < 2; ++n) _Pragma("unroll") for (int k = 0; k < 2; ++k) \
;         acc[ai][bj][m][n] = __builtin_amdgcn_mfma_f32_16x16x32_bf16(Bt[n][k], At[m][k], acc[ai][bj][m][n], 0, 0, 0); __builtin_amdgcn_s_setprio(0); } while (0)
; #define PG8_WAIT_V(n) asm volatile("s_waitcnt vmcnt(" #n ")" ::: "memory")
; #define PG8_WAIT_L(n) asm volatile("s_waitcnt lgkmcnt(" #n ")" ::: "memory")
; #define PG8_BAR __builtin_amdgcn_s_barrier()
; #define PG8_SCHED __builtin_amdgcn_sched_barrier(0)
; template <class Epi, class Sched, bool ALIGN_EPI = false, bool SP2 = false>
; __device__ __forceinline__ void gemm_phase(PG8_LAS unsigned char* lds, const Gemm g, const Sched& S, const Epi& E) {
;     ...
;             PG8_WAIT_V(8); PG8_WAIT_L(0); PG8_BAR; PG8_MMA(0, 0, At, B0); PG8_MMA(0, 1, At, B1); PG8_BAR; PG8_SCHED;
;             PG8_LDA(At, 0, 1); PG8_STAGE(PG8_SB(0, 0), b2, voffB); PG8_STAGE(PG8_SB(0, 1), b2 + hstep, voffB); PG8_STAGE(PG8_SA(0, 0), a2, voffA);
;             PG8_WAIT_V(8); PG8_WAIT_L(0); PG8_BAR; PG8_MMA(1, 0, At, B0); PG8_MMA(1, 1, At, B1); PG8_BAR; PG8_SCHED;
;             PG8_LDB(B0, 1, 0); PG8_LDB(B1, 1, 1); PG8_SCHED; PG8_LDA(At, 1, 0); PG8_STAGE(PG8_SA(0, 1), a2 + hstep, voffA);
;             PG8_WAIT_V(8); PG8_WAIT_L(0); PG8_BAR; PG8_MMA(0, 0, At, B0); PG8_MMA(0, 1, At, B1); PG8_BAR; PG8_SCHED;
	s_setprio 1
	s_waitcnt lgkmcnt(0)
	v_mfma_f32_16x16x32_bf16 v[60:63], v[154:157], v[186:189], 0
	v_mfma_f32_16x16x32_bf16 v[56:59], v[162:165], v[186:189], 0
	v_mfma_f32_16x16x32_bf16 v[52:55], v[154:157], v[194:197], 0
	v_mfma_f32_16x16x32_bf16 v[44:47], v[162:165], v[194:197], 0
	v_mfma_f32_16x16x32_bf16 v[36:39], v[154:157], v[202:205], 0
	v_mfma_f32_16x16x32_bf16 v[28:31], v[162:165], v[202:205], 0
	v_mfma_f32_16x16x32_bf16 v[20:23], v[154:157], v[214:217], 0
	v_mfma_f32_16x16x32_bf16 v[12:15], v[162:165], v[214:217], 0
	v_mfma_f32_16x16x32_bf16 v[60:63], v[158:161], v[190:193], v[60:63]
	v_mfma_f32_16x16x32_bf16 v[56:59], v[166:169], v[190:193], v[56:59]
	v_mfma_f32_16x16x32_bf16 v[52:55], v[158:161], v[198:201], v[52:55]
	v_mfma_f32_16x16x32_bf16 v[44:47], v[166:169], v[198:201], v[44:47]
	v_mfma_f32_16x16x32_bf16 v[36:39], v[158:161], v[210:213], v[36:39]
	v_mfma_f32_16x16x32_bf16 v[28:31], v[166:169], v[210:213], v[28:31]
	v_mfma_f32_16x16x32_bf16 v[20:23], v[158:161], v[218:221], v[20:23]
	v_mfma_f32_16x16x32_bf16 v[12:15], v[166:169], v[218:221], v[12:15]
	s_setprio 0
	s_setprio 1
	v_mfma_f32_16x16x32_bf16 v[48:51], v[170:173], v[186:189], 0
	v_mfma_f32_16x16x32_bf16 v[40:43], v[178:181], v[186:189], 0
	v_mfma_f32_16x16x32_bf16 v[32:35], v[170:173], v[194:197], 0
	v_mfma_f32_16x16x32_bf16 v[24:27], v[178:181], v[194:197], 0
	v_mfma_f32_16x16x32_bf16 v[16:19], v[170:173], v[202:205], 0
	v_mfma_f32_16x16x32_bf16 v[8:11], v[178:181], v[202:205], 0
	v_mfma_f32_16x16x32_bf16 v[4:7], v[170:173], v[214:217], 0
	v_mfma_f32_16x16x32_bf16 v[0:3], v[178:181], v[214:217], 0
	v_mfma_f32_16x16x32_bf16 v[48:51], v[174:177], v[190:193], v[48:51]
	v_mfma_f32_16x16x32_bf16 v[40:43], v[182:185], v[190:193], v[40:43]
	v_mfma_f32_16x16x32_bf16 v[32:35], v[174:177], v[198:201], v[32:35]
	v_mfma_f32_16x16x32_bf16 v[24:27], v[182:185], v[198:201], v[24:27]
	v_mfma_f32_16x16x32_bf16 v[16:19], v[174:177], v[210:213], v[16:19]
	v_mfma_f32_16x16x32_bf16 v[8:11], v[182:185], v[210:213], v[8:11]
	v_mfma_f32_16x16x32_bf16 v[4:7], v[174:177], v[218:221], v[4:7]
	v_mfma_f32_16x16x32_bf16 v[0:3], v[182:185], v[218:221], v[0:3]
	s_setprio 0
	s_barrier
	s_add_i32 s70, 0, 0x18000
	v_add_u32_e32 v144, s70, v148
	s_add_i32 s71, 0, 0x1c000
	ds_read_b128 v[154:157], v144
	ds_read_b128 v[158:161], v144 offset:1024
	ds_read_b128 v[162:165], v144 offset:2048
	ds_read_b128 v[166:169], v144 offset:3072
	v_add_u32_e32 v144, s71, v148
	ds_read_b128 v[170:173], v144
	ds_read_b128 v[174:177], v144 offset:1024
	ds_read_b128 v[178:181], v144 offset:2048
	ds_read_b128 v[182:185], v144 offset:3072
	s_add_u32 s38, s38, 0x80000
	s_addc_u32 s39, s39, 0
	s_mov_b32 m0, s48
	v_lshl_add_u64 v[226:227], s[38:39], 0, v[134:135]
	ds_read_b128 v[186:189], v152 offset:32768
	ds_read_b128 v[190:193], v152 offset:33792
	ds_read_b128 v[194:197], v152 offset:34816
	ds_read_b128 v[198:201], v152 offset:35840
	ds_read_b128 v[202:205], v152 offset:36864
	ds_read_b128 v[210:213], v152 offset:37888
	ds_read_b128 v[214:217], v152 offset:38912
	ds_read_b128 v[218:221], v152 offset:39936
	global_load_lds_dwordx4 v[226:227], off
	v_lshl_add_u64 v[226:227], s[38:39], 0, v[130:131]
	s_mov_b32 m0, s49
	s_nop 0
	global_load_lds_dwordx4 v[226:227], off
	s_waitcnt vmcnt(8)
	s_waitcnt lgkmcnt(0)
	s_barrier
	s_setprio 1
	s_waitcnt lgkmcnt(0)
	v_mfma_f32_16x16x32_bf16 v[124:127], v[154:157], v[186:189], v[124:127]
	v_mfma_f32_16x16x32_bf16 v[120:123], v[162:165], v[186:189], v[120:123]
	v_mfma_f32_16x16x32_bf16 v[116:119], v[154:157], v[194:197], v[116:119]
	v_mfma_f32_16x16x32_bf16 v[112:115], v[162:165], v[194:197], v[112:115]
	v_mfma_f32_16x16x32_bf16 v[100:103], v[154:157], v[202:205], v[100:103]
	v_mfma_f32_16x16x32_bf16 v[96:99], v[162:165], v[202:205], v[96:99]
	v_mfma_f32_16x16x32_bf16 v[80:83], v[154:157], v[214:217], v[80:83]
	v_mfma_f32_16x16x32_bf16 v[76:79], v[162:165], v[214:217], v[76:79]
	v_mfma_f32_16x16x32_bf16 v[124:127], v[158:161], v[190:193], v[124:127]
	v_mfma_f32_16x16x32_bf16 v[120:123], v[166:169], v[190:193], v[120:123]
	v_mfma_f32_16x16x32_bf16 v[116:119], v[158:161], v[198:201], v[116:119]
	v_mfma_f32_16x16x32_bf16 v[112:115], v[166:169], v[198:201], v[112:115]
	v_mfma_f32_16x16x32_bf16 v[100:103], v[158:161], v[210:213], v[100:103]
	v_mfma_f32_16x16x32_bf16 v[96:99], v[166:169], v[210:213], v[96:99]
	v_mfma_f32_16x16x32_bf16 v[80:83], v[158:161], v[218:221], v[80:83]
	v_mfma_f32_16x16x32_bf16 v[76:79], v[166:169], v[218:221], v[76:79]
	s_setprio 0
	s_setprio 1
	v_mfma_f32_16x16x32_bf16 v[108:111], v[170:173], v[186:189], v[108:111]
	v_mfma_f32_16x16x32_bf16 v[104:107], v[178:181], v[186:189], v[104:107]
	v_mfma_f32_16x16x32_bf16 v[92:95], v[170:173], v[194:197], v[92:95]
	v_mfma_f32_16x16x32_bf16 v[88:91], v[178:181], v[194:197], v[88:91]
	v_mfma_f32_16x16x32_bf16 v[84:87], v[170:173], v[202:205], v[84:87]
	v_mfma_f32_16x16x32_bf16 v[72:75], v[178:181], v[202:205], v[72:75]
	v_mfma_f32_16x16x32_bf16 v[68:71], v[170:173], v[214:217], v[68:71]
	v_mfma_f32_16x16x32_bf16 v[64:67], v[178:181], v[214:217], v[64:67]
	v_mfma_f32_16x16x32_bf16 v[108:111], v[174:177], v[190:193], v[108:111]
	v_mfma_f32_16x16x32_bf16 v[104:107], v[182:185], v[190:193], v[104:107]
	v_mfma_f32_16x16x32_bf16 v[92:95], v[174:177], v[198:201], v[92:95]
	v_mfma_f32_16x16x32_bf16 v[88:91], v[182:185], v[198:201], v[88:91]
	v_mfma_f32_16x16x32_bf16 v[84:87], v[174:177], v[210:213], v[84:87]
	v_mfma_f32_16x16x32_bf16 v[72:75], v[182:185], v[210:213], v[72:75]
	v_mfma_f32_16x16x32_bf16 v[68:71], v[174:177], v[218:221], v[68:71]
	v_mfma_f32_16x16x32_bf16 v[64:67], v[182:185], v[218:221], v[64:67]
	s_setprio 0
	s_barrier
; #define PG8_STAGE(bufoff, gbase, voff) do { _Pragma("unroll") for (int _i = 0; _i < 2; ++_i) \
;         __builtin_amdgcn_global_load_lds((const unsigned*)((const char*)(gbase) + (voff)[_i]), (PG8_LAS unsigned*)(lds + (bufoff) + ldsw + _i * 8192), 16, 0, 0); } while (0)
; #define PG8_LDA(dst, b, h) do { _Pragma("unroll") for (int m = 0; m < 4; ++m) _Pragma("unroll") for (int k = 0; k < 2; ++k) dst[m][k] = *(const PG8_LAS bf16x8*)(lds + PG8_SA(b, h) + aoff + m * 2048 + k * 1024); } while (0)
; #define PG8_LDB(dst, b, h) do { _Pragma("unroll") for (int n = 0; n < 2; ++n) _Pragma("unroll") for (int k = 0; k < 2; ++k) dst[n][k] = *(const PG8_LAS bf16x8*)(lds + PG8_SB(b, h) + boff + n * 2048 + k * 1024); } while (0)
; #define PG8_MMA(ai, bj, At, Bt) do { __builtin_amdgcn_s_setprio(1); _Pragma("unroll") for (int m = 0; m < 4; ++m) _Pragma("unroll") for (int n = 0; n < 2; ++n) _Pragma("unroll") for (int k = 0; k < 2; ++k) \
;         acc[ai][bj][m][n] = __builtin_amdgcn_mfma_f32_16x16x32_bf16(Bt[n][k], At[m][k], acc[ai][bj][m][n], 0, 0, 0); __builtin_amdgcn_s_setprio(0); } while (0)
; #define PG8_WAIT_V(n) asm volatile("s_waitcnt vmcnt(" #n ")" ::: "memory")
; #define PG8_WAIT_L(n) asm volatile("s_waitcnt lgkmcnt(" #n ")" ::: "memory")
; #define PG8_BAR __builtin_amdgcn_s_barrier()
; #define PG8_SCHED __builtin_amdgcn_sched_barrier(0)
; template <class Epi, class Sched, bool ALIGN_EPI = false, bool SP2 = false>
; __device__ __forceinline__ void gemm_phase(PG8_LAS unsigned char* lds, const Gemm g, const Sched& S, const Epi& E) {
;     ...
;         for (int t = 0; t < nt; t += 2) {
;     ...
;             PG8_LDB(B0, 1, 0); PG8_LDB(B1, 1, 1); PG8_SCHED; PG8_LDA(At, 1, 0); PG8_STAGE(PG8_SA(0, 1), a2 + hstep, voffA);
;             PG8_WAIT_V(8); PG8_WAIT_L(0); PG8_BAR; PG8_MMA(0, 0, At, B0); PG8_MMA(0, 1, At, B1); PG8_BAR; PG8_SCHED;
;             PG8_LDA(At, 1, 1); PG8_STAGE(PG8_SB(1, 0), b3, voffB); PG8_STAGE(PG8_SB(1, 1), b3 + hstep, voffB); PG8_STAGE(PG8_SA(1, 0), a3, voffA);
;             PG8_WAIT_V(8); PG8_WAIT_L(0); PG8_BAR; PG8_MMA(1, 0, At, B0); PG8_MMA(1, 1, At, B1); PG8_BAR; PG8_SCHED;
	s_add_i32 s38, s70, s44
	v_lshl_add_u64 v[146:147], v[146:147], 0, s[10:11]
	s_mov_b32 m0, s38
	ds_read_b128 v[186:189], v152 offset:49152
	ds_read_b128 v[190:193], v152 offset:50176
	ds_read_b128 v[194:197], v152 offset:51200
	ds_read_b128 v[198:201], v152 offset:52224
	ds_read_b128 v[202:205], v152 offset:53248
	ds_read_b128 v[210:213], v152 offset:54272
	ds_read_b128 v[214:217], v152 offset:55296
	ds_read_b128 v[218:221], v152 offset:56320
	global_load_lds_dwordx4 v[146:147], off
	s_add_i32 m0, s38, 0x2000
	s_add_u32 s36, s36, 0x80080
	v_lshl_add_u64 v[146:147], v[206:207], 0, s[10:11]
	s_addc_u32 s37, s37, 0
	s_add_i32 s38, s71, s44
	global_load_lds_dwordx4 v[146:147], off
	v_lshl_add_u64 v[146:147], s[36:37], 0, v[132:133]
	s_mov_b32 m0, s38
	s_nop 0
	global_load_lds_dwordx4 v[146:147], off
	v_lshl_add_u64 v[146:147], s[36:37], 0, v[128:129]
	s_add_i32 m0, s38, 0x2000
	s_nop 0
	global_load_lds_dwordx4 v[146:147], off
	v_lshl_add_u64 v[146:147], v[222:223], 0, s[10:11]
	s_mov_b32 m0, s55
	s_nop 0
	global_load_lds_dwordx4 v[146:147], off
	v_lshl_add_u64 v[146:147], v[224:225], 0, s[10:11]
	s_mov_b32 m0, s56
	s_nop 0
	global_load_lds_dwordx4 v[146:147], off
	s_waitcnt vmcnt(8)
	s_waitcnt lgkmcnt(0)
	s_barrier
	s_setprio 1
	s_waitcnt lgkmcnt(0)
	v_mfma_f32_16x16x32_bf16 v[60:63], v[154:157], v[186:189], v[60:63]
	v_mfma_f32_16x16x32_bf16 v[56:59], v[162:165], v[186:189], v[56:59]
	v_mfma_f32_16x16x32_bf16 v[52:55], v[154:157], v[194:197], v[52:55]
	v_mfma_f32_16x16x32_bf16 v[44:47], v[162:165], v[194:197], v[44:47]
	v_mfma_f32_16x16x32_bf16 v[36:39], v[154:157], v[202:205], v[36:39]
	v_mfma_f32_16x16x32_bf16 v[28:31], v[162:165], v[202:205], v[28:31]
	v_mfma_f32_16x16x32_bf16 v[20:23], v[154:157], v[214:217], v[20:23]
	v_mfma_f32_16x16x32_bf16 v[12:15], v[162:165], v[214:217], v[12:15]
	v_mfma_f32_16x16x32_bf16 v[60:63], v[158:161], v[190:193], v[60:63]
	v_mfma_f32_16x16x32_bf16 v[56:59], v[166:169], v[190:193], v[56:59]
	v_mfma_f32_16x16x32_bf16 v[52:55], v[158:161], v[198:201], v[52:55]
	v_mfma_f32_16x16x32_bf16 v[44:47], v[166:169], v[198:201], v[44:47]
	v_mfma_f32_16x16x32_bf16 v[36:39], v[158:161], v[210:213], v[36:39]
	v_mfma_f32_16x16x32_bf16 v[28:31], v[166:169], v[210:213], v[28:31]
	v_mfma_f32_16x16x32_bf16 v[20:23], v[158:161], v[218:221], v[20:23]
	v_mfma_f32_16x16x32_bf16 v[12:15], v[166:169], v[218:221], v[12:15]
	s_setprio 0
	s_setprio 1
	v_mfma_f32_16x16x32_bf16 v[48:51], v[170:173], v[186:189], v[48:51]
	v_mfma_f32_16x16x32_bf16 v[40:43], v[178:181], v[186:189], v[40:43]
	v_mfma_f32_16x16x32_bf16 v[32:35], v[170:173], v[194:197], v[32:35]
	v_mfma_f32_16x16x32_bf16 v[24:27], v[178:181], v[194:197], v[24:27]
	v_mfma_f32_16x16x32_bf16 v[16:19], v[170:173], v[202:205], v[16:19]
	v_mfma_f32_16x16x32_bf16 v[8:11], v[178:181], v[202:205], v[8:11]
	v_mfma_f32_16x16x32_bf16 v[4:7], v[170:173], v[214:217], v[4:7]
	v_mfma_f32_16x16x32_bf16 v[0:3], v[178:181], v[214:217], v[0:3]
	v_mfma_f32_16x16x32_bf16 v[48:51], v[174:177], v[190:193], v[48:51]
	v_mfma_f32_16x16x32_bf16 v[40:43], v[182:185], v[190:193], v[40:43]
	v_mfma_f32_16x16x32_bf16 v[32:35], v[174:177], v[198:201], v[32:35]
	v_mfma_f32_16x16x32_bf16 v[24:27], v[182:185], v[198:201], v[24:27]
	v_mfma_f32_16x16x32_bf16 v[16:19], v[174:177], v[210:213], v[16:19]
	v_mfma_f32_16x16x32_bf16 v[8:11], v[182:185], v[210:213], v[8:11]
	v_mfma_f32_16x16x32_bf16 v[4:7], v[174:177], v[218:221], v[4:7]
	v_mfma_f32_16x16x32_bf16 v[0:3], v[182:185], v[218:221], v[0:3]
	s_setprio 0
	s_barrier
	s_add_i32 s69, s69, 2
	s_add_u32 s34, s34, 0x100
	s_addc_u32 s35, s35, 0
	s_add_u32 s67, s67, 0x100
	s_addc_u32 s68, s68, 0
	s_cmp_gt_u32 s69, 29

; template <class Epi, class Sched, bool ALIGN_EPI = false, bool SP2 = false>
; __device__ __forceinline__ void gemm_phase(PG8_LAS unsigned char* lds, const Gemm g, const Sched& S, const Epi& E) {
;     ...
;         const bool has_next = S.next(ui + 1, nxt);
;         const char* nA = has_next ? (const char*)g.A + (size_t)nxt.pm * tstep : cA; const char* nB = has_next ? (const char*)g.Bt + (size_t)nxt.pn * tstep : cB;
;         for (int t = 0; t < nt; t += 2) {
;             const bool last = (t == nt - 2);
;             const char* a1 = cA + (size_t)(t + 1) * kstep;
;             const char* a2 = last ? nA : cA + (size_t)(t + 2) * kstep; const char* b2 = last ? nB : cB + (size_t)(t + 2) * kstep;
;             const char* a3 = a2 + kstep; const char* b3 = b2 + kstep;
;     ...
; #pragma unroll
;         for (int a = 0; a < 2; ++a)
; #pragma unroll
;             for (int b = 0; b < 2; ++b)
; #pragma unroll
;                 for (int m = 0; m < 4; ++m)
; #pragma unroll
;                     for (int n = 0; n < 2; ++n) acc[a][b][m][n] = (f32x4){0.f, 0.f, 0.f, 0.f};
;         cur = nxt; cA = nA; cB = nB; ++ui;
.LBB0_520:
	s_ashr_i32 s19, s18, 31
	s_lshl_b64 s[20:21], s[18:19], 20
	s_add_u32 s20, s35, s20
	s_addc_u32 s21, s36, s21
	s_and_b64 s[22:23], s[40:41], exec
	s_cselect_b32 s19, s21, s27
	s_cselect_b32 s58, s20, s26
	s_ashr_i32 s17, s16, 31
	s_lshl_b64 s[22:23], s[16:17], 20
	s_add_u32 s22, s37, s22
	s_addc_u32 s23, s38, s23
	s_and_b64 s[30:31], s[40:41], exec
	s_cselect_b32 s17, s23, s29
	s_cselect_b32 s59, s22, s28
	s_add_u32 s26, s26, 0x80080
	s_addc_u32 s27, s27, 0
	s_add_u32 s60, s28, 0x100

; template <class Epi, class Sched, bool ALIGN_EPI = false, bool SP2 = false>
; __device__ __forceinline__ void gemm_phase(PG8_LAS unsigned char* lds, const Gemm g, const Sched& S, const Epi& E) {
;     ...
; #pragma unroll
;         for (int a = 0; a < 2; ++a)
; #pragma unroll
;             for (int b = 0; b < 2; ++b)
; #pragma unroll
;                 for (int m = 0; m < 4; ++m)
; #pragma unroll
;                     for (int n = 0; n < 2; ++n) acc[a][b][m][n] = (f32x4){0.f, 0.f, 0.f, 0.f};
;         cur = nxt; cA = nA; cB = nB; ++ui;
	s_addc_u32 s61, s29, 0
	s_mov_b32 s62, -2


; #define PG8_STAGE(bufoff, gbase, voff) do { _Pragma("unroll") for (int _i = 0; _i < 2; ++_i) \
;         __builtin_amdgcn_global_load_lds((const unsigned*)((const char*)(gbase) + (voff)[_i]), (PG8_LAS unsigned*)(lds + (bufoff) + ldsw + _i * 8192), 16, 0, 0); } while (0)
; #define PG8_LDA(dst, b, h) do { _Pragma("unroll") for (int m = 0; m < 4; ++m) _Pragma("unroll") for (int k = 0; k < 2; ++k) dst[m][k] = *(const PG8_LAS bf16x8*)(lds + PG8_SA(b, h) + aoff + m * 2048 + k * 1024); } while (0)
; #define PG8_LDB(dst, b, h) do { _Pragma("unroll") for (int n = 0; n < 2; ++n) _Pragma("unroll") for (int k = 0; k < 2; ++k) dst[n][k] = *(const PG8_LAS bf16x8*)(lds + PG8_SB(b, h) + boff + n * 2048 + k * 1024); } while (0)
; #define PG8_MMA(ai, bj, At, Bt) do { __builtin_amdgcn_s_setprio(1); _Pragma("unroll") for (int m = 0; m < 4; ++m) _Pragma("unroll") for (int n = 0; n < 2; ++n) _Pragma("unroll") for (int k = 0; k < 2; ++k) \
;         acc[ai][bj][m][n] = __builtin_amdgcn_mfma_f32_16x16x32_bf16(Bt[n][k], At[m][k], acc[ai][bj][m][n], 0, 0, 0); __builtin_amdgcn_s_setprio(0); } while (0)
; #define PG8_WAIT_V(n) asm volatile("s_waitcnt vmcnt(" #n ")" ::: "memory")
; #define PG8_BAR __builtin_amdgcn_s_barrier()
; template <class Epi, class Sched, bool ALIGN_EPI = false, bool SP2 = false>
; __device__ __forceinline__ void gemm_phase(PG8_LAS unsigned char* lds, const Gemm g, const Sched& S, const Epi& E) {
;     ...
;         for (int t = 0; t < nt; t += 2) {
;             const bool last = (t == nt - 2);
;             const char* a1 = cA + (size_t)(t + 1) * kstep;
;             const char* a2 = last ? nA : cA + (size_t)(t + 2) * kstep; const char* b2 = last ? nB : cB + (size_t)(t + 2) * kstep;
;             const char* a3 = a2 + kstep; const char* b3 = b2 + kstep;
;             if (last && has_next) S.a_ready(nxt);
;             if constexpr (SP2) {
;             PG8_LDB(B0, 0, 0); PG8_LDB(B1, 0, 1); PG8_SCHED; PG8_LDA(At, 0, 0); PG8_STAGE(PG8_SA(1, 1), a1 + hstep, voffA);
;             PG8_WAIT_V(8); PG8_WAIT_L(0); PG8_BAR; PG8_MMA(0, 0, At, B0); PG8_MMA(0, 1, At, B1); PG8_BAR; PG8_SCHED;
;             PG8_LDA(At, 0, 1); PG8_STAGE(PG8_SB(0, 0), b2, voffB); PG8_STAGE(PG8_SB(0, 1), b2 + hstep, voffB); PG8_STAGE(PG8_SA(0, 0), a2, voffA);
;             PG8_WAIT_V(8); PG8_WAIT_L(0); PG8_BAR; PG8_MMA(1, 0, At, B0); PG8_MMA(1, 1, At, B1); PG8_BAR; PG8_SCHED;
	s_add_u32 s28, s26, 0xfff80080
	s_addc_u32 s29, s27, -1
	s_add_i32 s68, 0, 0x10000
	s_cmp_eq_u32 s62, 28
	s_cselect_b32 s31, s19, s29
	s_cselect_b32 s30, s58, s28
	v_add_u32_e32 v130, s68, v156
	s_cselect_b32 s29, s17, s61
	s_cselect_b32 s28, s59, s60
	s_add_i32 s74, 0, 0x14000
	ds_read_b128 v[160:163], v130
	ds_read_b128 v[164:167], v130 offset:1024
	ds_read_b128 v[168:171], v130 offset:2048
	ds_read_b128 v[172:175], v130 offset:3072
	v_add_u32_e32 v130, s74, v156
	ds_read_b128 v[176:179], v130
	ds_read_b128 v[180:183], v130 offset:1024
	ds_read_b128 v[184:187], v130 offset:2048
	ds_read_b128 v[188:191], v130 offset:3072
	v_lshl_add_u64 v[130:131], s[26:27], 0, v[148:149]
	s_add_i32 m0, s42, 0xc000
	ds_read_b128 v[192:195], v158
	ds_read_b128 v[196:199], v158 offset:1024
	ds_read_b128 v[200:203], v158 offset:2048
	ds_read_b128 v[204:207], v158 offset:3072
	ds_read_b128 v[218:221], v158 offset:4096
	ds_read_b128 v[222:225], v158 offset:5120
	ds_read_b128 v[226:229], v158 offset:6144
	ds_read_b128 v[230:233], v158 offset:7168
	global_load_lds_dwordx4 v[130:131], off
	v_lshl_add_u64 v[130:131], s[26:27], 0, v[150:151]
	s_add_i32 m0, s42, 0xe000
	s_nop 0
	global_load_lds_dwordx4 v[130:131], off
	s_waitcnt vmcnt(8)
	s_waitcnt lgkmcnt(0)
	s_barrier
	s_setprio 1
	s_waitcnt lgkmcnt(0)
	v_mfma_f32_16x16x32_bf16 v[124:127], v[160:163], v[192:195], 0
	v_mfma_f32_16x16x32_bf16 v[120:123], v[168:171], v[192:195], 0
	v_mfma_f32_16x16x32_bf16 v[116:119], v[160:163], v[200:203], 0
	v_mfma_f32_16x16x32_bf16 v[112:115], v[168:171], v[200:203], 0
	v_mfma_f32_16x16x32_bf16 v[100:103], v[160:163], v[218:221], 0
	v_mfma_f32_16x16x32_bf16 v[96:99], v[168:171], v[218:221], 0
	v_mfma_f32_16x16x32_bf16 v[80:83], v[160:163], v[226:229], 0
	v_mfma_f32_16x16x32_bf16 v[76:79], v[168:171], v[226:229], 0
	v_mfma_f32_16x16x32_bf16 v[124:127], v[164:167], v[196:199], v[124:127]
	v_mfma_f32_16x16x32_bf16 v[120:123], v[172:175], v[196:199], v[120:123]
	v_mfma_f32_16x16x32_bf16 v[116:119], v[164:167], v[204:207], v[116:119]
	v_mfma_f32_16x16x32_bf16 v[112:115], v[172:175], v[204:207], v[112:115]
	v_mfma_f32_16x16x32_bf16 v[100:103], v[164:167], v[222:225], v[100:103]
	v_mfma_f32_16x16x32_bf16 v[96:99], v[172:175], v[222:225], v[96:99]
	v_mfma_f32_16x16x32_bf16 v[80:83], v[164:167], v[230:233], v[80:83]
	v_mfma_f32_16x16x32_bf16 v[76:79], v[172:175], v[230:233], v[76:79]
	s_setprio 0
	s_setprio 1
	v_mfma_f32_16x16x32_bf16 v[108:111], v[176:179], v[192:195], 0
	v_mfma_f32_16x16x32_bf16 v[104:107], v[184:187], v[192:195], 0
	v_mfma_f32_16x16x32_bf16 v[92:95], v[176:179], v[200:203], 0
	v_mfma_f32_16x16x32_bf16 v[88:91], v[184:187], v[200:203], 0
	v_mfma_f32_16x16x32_bf16 v[84:87], v[176:179], v[218:221], 0
	v_mfma_f32_16x16x32_bf16 v[72:75], v[184:187], v[218:221], 0
	v_mfma_f32_16x16x32_bf16 v[68:71], v[176:179], v[226:229], 0
	v_mfma_f32_16x16x32_bf16 v[64:67], v[184:187], v[226:229], 0
	v_mfma_f32_16x16x32_bf16 v[108:111], v[180:183], v[196:199], v[108:111]
	v_mfma_f32_16x16x32_bf16 v[104:107], v[188:191], v[196:199], v[104:107]
	v_mfma_f32_16x16x32_bf16 v[92:95], v[180:183], v[204:207], v[92:95]
	v_mfma_f32_16x16x32_bf16 v[88:91], v[188:191], v[204:207], v[88:91]
	v_mfma_f32_16x16x32_bf16 v[84:87], v[180:183], v[222:225], v[84:87]
	v_mfma_f32_16x16x32_bf16 v[72:75], v[188:191], v[222:225], v[72:75]
	v_mfma_f32_16x16x32_bf16 v[68:71], v[180:183], v[230:233], v[68:71]
	v_mfma_f32_16x16x32_bf16 v[64:67], v[188:191], v[230:233], v[64:67]
	s_setprio 0
	s_barrier
	s_add_i32 s68, s68, s39
	v_lshl_add_u64 v[130:131], s[28:29], 0, v[128:129]
	s_mov_b32 m0, s68
	ds_read_b128 v[192:195], v158 offset:16384
	ds_read_b128 v[196:199], v158 offset:17408
	ds_read_b128 v[200:203], v158 offset:18432
	ds_read_b128 v[204:207], v158 offset:19456
	ds_read_b128 v[218:221], v158 offset:20480
	ds_read_b128 v[222:225], v158 offset:21504
	ds_read_b128 v[226:229], v158 offset:22528
	ds_read_b128 v[230:233], v158 offset:23552
	global_load_lds_dwordx4 v[130:131], off
	s_add_i32 m0, s68, 0x2000
	s_add_u32 s68, s28, 0x80000
	v_lshl_add_u64 v[132:133], s[28:29], 0, v[142:143]
	s_addc_u32 s69, s29, 0
	s_add_i32 s74, s74, s39
	global_load_lds_dwordx4 v[132:133], off
	v_lshl_add_u64 v[154:155], s[68:69], 0, v[128:129]
	s_mov_b32 m0, s74
	v_lshl_add_u64 v[234:235], s[30:31], 0, v[144:145]
	global_load_lds_dwordx4 v[154:155], off
	v_lshl_add_u64 v[154:155], s[68:69], 0, v[142:143]
	s_add_i32 m0, s74, 0x2000
	s_nop 0
	global_load_lds_dwordx4 v[154:155], off
	v_lshl_add_u64 v[154:155], s[30:31], 0, v[146:147]
	s_mov_b32 m0, s42
	s_nop 0
	global_load_lds_dwordx4 v[154:155], off
	s_mov_b32 m0, s43
	s_nop 0
	global_load_lds_dwordx4 v[234:235], off
	s_waitcnt vmcnt(8)
	s_waitcnt lgkmcnt(0)
	s_barrier
; #define PG8_STAGE(bufoff, gbase, voff) do { _Pragma("unroll") for (int _i = 0; _i < 2; ++_i) \
;         __builtin_amdgcn_global_load_lds((const unsigned*)((const char*)(gbase) + (voff)[_i]), (PG8_LAS unsigned*)(lds + (bufoff) + ldsw + _i * 8192), 16, 0, 0); } while (0)
; #define PG8_LDA(dst, b, h) do { _Pragma("unroll") for (int m = 0; m < 4; ++m) _Pragma("unroll") for (int k = 0; k < 2; ++k) dst[m][k] = *(const PG8_LAS bf16x8*)(lds + PG8_SA(b, h) + aoff + m * 2048 + k * 1024); } while (0)
; #define PG8_LDB(dst, b, h) do { _Pragma("unroll") for (int n = 0; n < 2; ++n) _Pragma("unroll") for (int k = 0; k < 2; ++k) dst[n][k] = *(const PG8_LAS bf16x8*)(lds + PG8_SB(b, h) + boff + n * 2048 + k * 1024); } while (0)
; #define PG8_MMA(ai, bj, At, Bt) do { __builtin_amdgcn_s_setprio(1); _Pragma("unroll") for (int m = 0; m < 4; ++m) _Pragma("unroll") for (int n = 0; n < 2; ++n) _Pragma("unroll") for (int k = 0; k < 2; ++k) \
;         acc[ai][bj][m][n] = __builtin_amdgcn_mfma_f32_16x16x32_bf16(Bt[n][k], At[m][k], acc[ai][bj][m][n], 0, 0, 0); __builtin_amdgcn_s_setprio(0); } while (0)
; #define PG8_WAIT_V(n) asm volatile("s_waitcnt vmcnt(" #n ")" ::: "memory")
; #define PG8_WAIT_L(n) asm volatile("s_waitcnt lgkmcnt(" #n ")" ::: "memory")
; #define PG8_BAR __builtin_amdgcn_s_barrier()
; #define PG8_SCHED __builtin_amdgcn_sched_barrier(0)
; template <class Epi, class Sched, bool ALIGN_EPI = false, bool SP2 = false>
; __device__ __forceinline__ void gemm_phase(PG8_LAS unsigned char* lds, const Gemm g, const Sched& S, const Epi& E) {
;     ...
;             PG8_WAIT_V(8); PG8_WAIT_L(0); PG8_BAR; PG8_MMA(1, 0, At, B0); PG8_MMA(1, 1, At, B1); PG8_BAR; PG8_SCHED;
;             PG8_LDB(B0, 1, 0); PG8_LDB(B1, 1, 1); PG8_SCHED; PG8_LDA(At, 1, 0); PG8_STAGE(PG8_SA(0, 1), a2 + hstep, voffA);
;             PG8_WAIT_V(8); PG8_WAIT_L(0); PG8_BAR; PG8_MMA(0, 0, At, B0); PG8_MMA(0, 1, At, B1); PG8_BAR; PG8_SCHED;
	s_setprio 1
	s_waitcnt lgkmcnt(0)
	v_mfma_f32_16x16x32_bf16 v[60:63], v[160:163], v[192:195], 0
	v_mfma_f32_16x16x32_bf16 v[56:59], v[168:171], v[192:195], 0
	v_mfma_f32_16x16x32_bf16 v[52:55], v[160:163], v[200:203], 0
	v_mfma_f32_16x16x32_bf16 v[44:47], v[168:171], v[200:203], 0
	v_mfma_f32_16x16x32_bf16 v[36:39], v[160:163], v[218:221], 0
	v_mfma_f32_16x16x32_bf16 v[28:31], v[168:171], v[218:221], 0
	v_mfma_f32_16x16x32_bf16 v[20:23], v[160:163], v[226:229], 0
	v_mfma_f32_16x16x32_bf16 v[12:15], v[168:171], v[226:229], 0
	v_mfma_f32_16x16x32_bf16 v[60:63], v[164:167], v[196:199], v[60:63]
	v_mfma_f32_16x16x32_bf16 v[56:59], v[172:175], v[196:199], v[56:59]
	v_mfma_f32_16x16x32_bf16 v[52:55], v[164:167], v[204:207], v[52:55]
	v_mfma_f32_16x16x32_bf16 v[44:47], v[172:175], v[204:207], v[44:47]
	v_mfma_f32_16x16x32_bf16 v[36:39], v[164:167], v[222:225], v[36:39]
	v_mfma_f32_16x16x32_bf16 v[28:31], v[172:175], v[222:225], v[28:31]
	v_mfma_f32_16x16x32_bf16 v[20:23], v[164:167], v[230:233], v[20:23]
	v_mfma_f32_16x16x32_bf16 v[12:15], v[172:175], v[230:233], v[12:15]
	s_setprio 0
	s_setprio 1
	v_mfma_f32_16x16x32_bf16 v[48:51], v[176:179], v[192:195], 0
	v_mfma_f32_16x16x32_bf16 v[40:43], v[184:187], v[192:195], 0
	v_mfma_f32_16x16x32_bf16 v[32:35], v[176:179], v[200:203], 0
	v_mfma_f32_16x16x32_bf16 v[24:27], v[184:187], v[200:203], 0
	v_mfma_f32_16x16x32_bf16 v[16:19], v[176:179], v[218:221], 0
	v_mfma_f32_16x16x32_bf16 v[8:11], v[184:187], v[218:221], 0
	v_mfma_f32_16x16x32_bf16 v[4:7], v[176:179], v[226:229], 0
	v_mfma_f32_16x16x32_bf16 v[0:3], v[184:187], v[226:229], 0
	v_mfma_f32_16x16x32_bf16 v[48:51], v[180:183], v[196:199], v[48:51]
	v_mfma_f32_16x16x32_bf16 v[40:43], v[188:191], v[196:199], v[40:43]
	v_mfma_f32_16x16x32_bf16 v[32:35], v[180:183], v[204:207], v[32:35]
	v_mfma_f32_16x16x32_bf16 v[24:27], v[188:191], v[204:207], v[24:27]
	v_mfma_f32_16x16x32_bf16 v[16:19], v[180:183], v[222:225], v[16:19]
	v_mfma_f32_16x16x32_bf16 v[8:11], v[188:191], v[222:225], v[8:11]
	v_mfma_f32_16x16x32_bf16 v[4:7], v[180:183], v[230:233], v[4:7]
	v_mfma_f32_16x16x32_bf16 v[0:3], v[188:191], v[230:233], v[0:3]
	s_setprio 0
	s_barrier
	s_add_i32 s68, 0, 0x18000
	v_add_u32_e32 v134, s68, v156
	s_add_i32 s69, 0, 0x1c000
	ds_read_b128 v[160:163], v134
	ds_read_b128 v[164:167], v134 offset:1024
	ds_read_b128 v[168:171], v134 offset:2048
	ds_read_b128 v[172:175], v134 offset:3072
	v_add_u32_e32 v134, s69, v156
	ds_read_b128 v[176:179], v134
	ds_read_b128 v[180:183], v134 offset:1024
	ds_read_b128 v[184:187], v134 offset:2048
	ds_read_b128 v[188:191], v134 offset:3072
	s_add_u32 s30, s30, 0x80000
	s_addc_u32 s31, s31, 0
	s_mov_b32 m0, s44
	v_lshl_add_u64 v[236:237], s[30:31], 0, v[146:147]
	ds_read_b128 v[192:195], v158 offset:32768
	ds_read_b128 v[196:199], v158 offset:33792
	ds_read_b128 v[200:203], v158 offset:34816
	ds_read_b128 v[204:207], v158 offset:35840
	ds_read_b128 v[218:221], v158 offset:36864
	ds_read_b128 v[222:225], v158 offset:37888
	ds_read_b128 v[226:229], v158 offset:38912
	ds_read_b128 v[230:233], v158 offset:39936
	global_load_lds_dwordx4 v[236:237], off
	v_lshl_add_u64 v[236:237], s[30:31], 0, v[144:145]
	s_mov_b32 m0, s45
	s_nop 0
	global_load_lds_dwordx4 v[236:237], off
	s_waitcnt vmcnt(8)
	s_waitcnt lgkmcnt(0)
	s_barrier
	s_setprio 1
	s_waitcnt lgkmcnt(0)
	v_mfma_f32_16x16x32_bf16 v[124:127], v[160:163], v[192:195], v[124:127]
	v_mfma_f32_16x16x32_bf16 v[120:123], v[168:171], v[192:195], v[120:123]
	v_mfma_f32_16x16x32_bf16 v[116:119], v[160:163], v[200:203], v[116:119]
	v_mfma_f32_16x16x32_bf16 v[112:115], v[168:171], v[200:203], v[112:115]
	v_mfma_f32_16x16x32_bf16 v[100:103], v[160:163], v[218:221], v[100:103]
	v_mfma_f32_16x16x32_bf16 v[96:99], v[168:171], v[218:221], v[96:99]
	v_mfma_f32_16x16x32_bf16 v[80:83], v[160:163], v[226:229], v[80:83]
	v_mfma_f32_16x16x32_bf16 v[76:79], v[168:171], v[226:229], v[76:79]
	v_mfma_f32_16x16x32_bf16 v[124:127], v[164:167], v[196:199], v[124:127]
	v_mfma_f32_16x16x32_bf16 v[120:123], v[172:175], v[196:199], v[120:123]
	v_mfma_f32_16x16x32_bf16 v[116:119], v[164:167], v[204:207], v[116:119]
	v_mfma_f32_16x16x32_bf16 v[112:115], v[172:175], v[204:207], v[112:115]
	v_mfma_f32_16x16x32_bf16 v[100:103], v[164:167], v[222:225], v[100:103]
	v_mfma_f32_16x16x32_bf16 v[96:99], v[172:175], v[222:225], v[96:99]
	v_mfma_f32_16x16x32_bf16 v[80:83], v[164:167], v[230:233], v[80:83]
	v_mfma_f32_16x16x32_bf16 v[76:79], v[172:175], v[230:233], v[76:79]
	s_setprio 0
	s_setprio 1
	v_mfma_f32_16x16x32_bf16 v[108:111], v[176:179], v[192:195], v[108:111]
	v_mfma_f32_16x16x32_bf16 v[104:107], v[184:187], v[192:195], v[104:107]
	v_mfma_f32_16x16x32_bf16 v[92:95], v[176:179], v[200:203], v[92:95]
	v_mfma_f32_16x16x32_bf16 v[88:91], v[184:187], v[200:203], v[88:91]
	v_mfma_f32_16x16x32_bf16 v[84:87], v[176:179], v[218:221], v[84:87]
	v_mfma_f32_16x16x32_bf16 v[72:75], v[184:187], v[218:221], v[72:75]
	v_mfma_f32_16x16x32_bf16 v[68:71], v[176:179], v[226:229], v[68:71]
	v_mfma_f32_16x16x32_bf16 v[64:67], v[184:187], v[226:229], v[64:67]
	v_mfma_f32_16x16x32_bf16 v[108:111], v[180:183], v[196:199], v[108:111]
	v_mfma_f32_16x16x32_bf16 v[104:107], v[188:191], v[196:199], v[104:107]
	v_mfma_f32_16x16x32_bf16 v[92:95], v[180:183], v[204:207], v[92:95]
	v_mfma_f32_16x16x32_bf16 v[88:91], v[188:191], v[204:207], v[88:91]
	v_mfma_f32_16x16x32_bf16 v[84:87], v[180:183], v[222:225], v[84:87]
	v_mfma_f32_16x16x32_bf16 v[72:75], v[188:191], v[222:225], v[72:75]
	v_mfma_f32_16x16x32_bf16 v[68:71], v[180:183], v[230:233], v[68:71]
	v_mfma_f32_16x16x32_bf16 v[64:67], v[188:191], v[230:233], v[64:67]
	s_setprio 0
	s_barrier
; #define PG8_STAGE(bufoff, gbase, voff) do { _Pragma("unroll") for (int _i = 0; _i < 2; ++_i) \
;         __builtin_amdgcn_global_load_lds((const unsigned*)((const char*)(gbase) + (voff)[_i]), (PG8_LAS unsigned*)(lds + (bufoff) + ldsw + _i * 8192), 16, 0, 0); } while (0)
; #define PG8_LDA(dst, b, h) do { _Pragma("unroll") for (int m = 0; m < 4; ++m) _Pragma("unroll") for (int k = 0; k < 2; ++k) dst[m][k] = *(const PG8_LAS bf16x8*)(lds + PG8_SA(b, h) + aoff + m * 2048 + k * 1024); } while (0)
; #define PG8_MMA(ai, bj, At, Bt) do { __builtin_amdgcn_s_setprio(1); _Pragma("unroll") for (int m = 0; m < 4; ++m) _Pragma("unroll") for (int n = 0; n < 2; ++n) _Pragma("unroll") for (int k = 0; k < 2; ++k) \
;         acc[ai][bj][m][n] = __builtin_amdgcn_mfma_f32_16x16x32_bf16(Bt[n][k], At[m][k], acc[ai][bj][m][n], 0, 0, 0); __builtin_amdgcn_s_setprio(0); } while (0)
; #define PG8_WAIT_V(n) asm volatile("s_waitcnt vmcnt(" #n ")" ::: "memory")
; #define PG8_WAIT_L(n) asm volatile("s_waitcnt lgkmcnt(" #n ")" ::: "memory")
; #define PG8_BAR __builtin_amdgcn_s_barrier()
; #define PG8_SCHED __builtin_amdgcn_sched_barrier(0)
; template <class Epi, class Sched, bool ALIGN_EPI = false, bool SP2 = false>
; __device__ __forceinline__ void gemm_phase(PG8_LAS unsigned char* lds, const Gemm g, const Sched& S, const Epi& E) {
;     ...
;         for (int t = 0; t < nt; t += 2) {
;     ...
;             PG8_LDA(At, 1, 1); PG8_STAGE(PG8_SB(1, 0), b3, voffB); PG8_STAGE(PG8_SB(1, 1), b3 + hstep, voffB); PG8_STAGE(PG8_SA(1, 0), a3, voffA);
;             PG8_WAIT_V(8); PG8_WAIT_L(0); PG8_BAR; PG8_MMA(1, 0, At, B0); PG8_MMA(1, 1, At, B1); PG8_BAR; PG8_SCHED;
	s_add_i32 s30, s68, s39
	v_lshl_add_u64 v[130:131], v[130:131], 0, s[78:79]
	s_mov_b32 m0, s30
	ds_read_b128 v[192:195], v158 offset:49152
	ds_read_b128 v[196:199], v158 offset:50176
	ds_read_b128 v[200:203], v158 offset:51200
	ds_read_b128 v[204:207], v158 offset:52224
	ds_read_b128 v[218:221], v158 offset:53248
	ds_read_b128 v[222:225], v158 offset:54272
	ds_read_b128 v[226:229], v158 offset:55296
	ds_read_b128 v[230:233], v158 offset:56320
	global_load_lds_dwordx4 v[130:131], off
	s_add_i32 m0, s30, 0x2000
	s_add_u32 s28, s28, 0x80080
	v_lshl_add_u64 v[130:131], v[132:133], 0, s[78:79]
	s_addc_u32 s29, s29, 0
	s_add_i32 s30, s69, s39
	global_load_lds_dwordx4 v[130:131], off
	v_lshl_add_u64 v[130:131], s[28:29], 0, v[128:129]
	s_mov_b32 m0, s30
	s_nop 0
	global_load_lds_dwordx4 v[130:131], off
	v_lshl_add_u64 v[130:131], s[28:29], 0, v[142:143]
	s_add_i32 m0, s30, 0x2000
	s_nop 0
	global_load_lds_dwordx4 v[130:131], off
	v_lshl_add_u64 v[130:131], v[154:155], 0, s[78:79]
	s_mov_b32 m0, s55
	s_nop 0
	global_load_lds_dwordx4 v[130:131], off
	v_lshl_add_u64 v[130:131], v[234:235], 0, s[78:79]
	s_mov_b32 m0, s56
	s_nop 0
	global_load_lds_dwordx4 v[130:131], off
	s_waitcnt vmcnt(8)
	s_waitcnt lgkmcnt(0)
	s_barrier
	s_setprio 1
	s_waitcnt lgkmcnt(0)
	v_mfma_f32_16x16x32_bf16 v[60:63], v[160:163], v[192:195], v[60:63]
	v_mfma_f32_16x16x32_bf16 v[56:59], v[168:171], v[192:195], v[56:59]
	v_mfma_f32_16x16x32_bf16 v[52:55], v[160:163], v[200:203], v[52:55]
	v_mfma_f32_16x16x32_bf16 v[44:47], v[168:171], v[200:203], v[44:47]
	v_mfma_f32_16x16x32_bf16 v[36:39], v[160:163], v[218:221], v[36:39]
	v_mfma_f32_16x16x32_bf16 v[28:31], v[168:171], v[218:221], v[28:31]
	v_mfma_f32_16x16x32_bf16 v[20:23], v[160:163], v[226:229], v[20:23]
	v_mfma_f32_16x16x32_bf16 v[12:15], v[168:171], v[226:229], v[12:15]
	v_mfma_f32_16x16x32_bf16 v[60:63], v[164:167], v[196:199], v[60:63]
	v_mfma_f32_16x16x32_bf16 v[56:59], v[172:175], v[196:199], v[56:59]
	v_mfma_f32_16x16x32_bf16 v[52:55], v[164:167], v[204:207], v[52:55]
	v_mfma_f32_16x16x32_bf16 v[44:47], v[172:175], v[204:207], v[44:47]
	v_mfma_f32_16x16x32_bf16 v[36:39], v[164:167], v[222:225], v[36:39]
	v_mfma_f32_16x16x32_bf16 v[28:31], v[172:175], v[222:225], v[28:31]
	v_mfma_f32_16x16x32_bf16 v[20:23], v[164:167], v[230:233], v[20:23]
	v_mfma_f32_16x16x32_bf16 v[12:15], v[172:175], v[230:233], v[12:15]
	s_setprio 0
	s_setprio 1
	v_mfma_f32_16x16x32_bf16 v[48:51], v[176:179], v[192:195], v[48:51]
	v_mfma_f32_16x16x32_bf16 v[40:43], v[184:187], v[192:195], v[40:43]
	v_mfma_f32_16x16x32_bf16 v[32:35], v[176:179], v[200:203], v[32:35]
	v_mfma_f32_16x16x32_bf16 v[24:27], v[184:187], v[200:203], v[24:27]
	v_mfma_f32_16x16x32_bf16 v[16:19], v[176:179], v[218:221], v[16:19]
	v_mfma_f32_16x16x32_bf16 v[8:11], v[184:187], v[218:221], v[8:11]
	v_mfma_f32_16x16x32_bf16 v[4:7], v[176:179], v[226:229], v[4:7]
	v_mfma_f32_16x16x32_bf16 v[0:3], v[184:187], v[226:229], v[0:3]
	v_mfma_f32_16x16x32_bf16 v[48:51], v[180:183], v[196:199], v[48:51]
	v_mfma_f32_16x16x32_bf16 v[40:43], v[188:191], v[196:199], v[40:43]
	v_mfma_f32_16x16x32_bf16 v[32:35], v[180:183], v[204:207], v[32:35]
	v_mfma_f32_16x16x32_bf16 v[24:27], v[188:191], v[204:207], v[24:27]
	v_mfma_f32_16x16x32_bf16 v[16:19], v[180:183], v[222:225], v[16:19]
	v_mfma_f32_16x16x32_bf16 v[8:11], v[188:191], v[222:225], v[8:11]
	v_mfma_f32_16x16x32_bf16 v[4:7], v[180:183], v[230:233], v[4:7]
	v_mfma_f32_16x16x32_bf16 v[0:3], v[188:191], v[230:233], v[0:3]
	s_setprio 0
	s_barrier
	s_add_i32 s62, s62, 2
	s_add_u32 s26, s26, 0x100
	s_addc_u32 s27, s27, 0
	s_add_u32 s60, s60, 0x100
	s_addc_u32 s61, s61, 0
	s_cmp_gt_u32 s62, 29

; template <class Epi, class Sched, bool ALIGN_EPI = false, bool SP2 = false>
; __device__ __forceinline__ void gemm_phase(PG8_LAS unsigned char* lds, const Gemm g, const Sched& S, const Epi& E) {
;     ...
;         const bool has_next = S.next(ui + 1, nxt);
;         const char* nA = has_next ? (const char*)g.A + (size_t)nxt.pm * tstep : cA; const char* nB = has_next ? (const char*)g.Bt + (size_t)nxt.pn * tstep : cB;
;         for (int t = 0; t < nt; t += 2) {
;             const bool last = (t == nt - 2);
;             const char* a1 = cA + (size_t)(t + 1) * kstep;
;             const char* a2 = last ? nA : cA + (size_t)(t + 2) * kstep; const char* b2 = last ? nB : cB + (size_t)(t + 2) * kstep;
;             const char* a3 = a2 + kstep; const char* b3 = b2 + kstep;
;     ...
; #pragma unroll
;         for (int a = 0; a < 2; ++a)
; #pragma unroll
;             for (int b = 0; b < 2; ++b)
; #pragma unroll
;                 for (int m = 0; m < 4; ++m)
; #pragma unroll
;                     for (int n = 0; n < 2; ++n) acc[a][b][m][n] = (f32x4){0.f, 0.f, 0.f, 0.f};
;         cur = nxt; cA = nA; cB = nB; ++ui;
.LBB0_817:
	s_ashr_i32 s31, s30, 31
	s_lshl_b64 s[26:27], s[30:31], 20
	s_add_u32 s34, s12, s26
	s_addc_u32 s35, s13, s27
	s_and_b64 s[26:27], s[42:43], exec
	s_cselect_b32 s21, s35, s25
	s_cselect_b32 s31, s34, s24
	s_ashr_i32 s29, s28, 31
	s_lshl_b64 s[26:27], s[28:29], 20
	s_add_u32 s26, s39, s26
	s_addc_u32 s27, s54, s27
	s_and_b64 s[68:69], s[42:43], exec
	s_cselect_b32 s29, s27, s81
	s_cselect_b32 s37, s26, s80
	s_add_u32 s68, s80, 0x100

; template <class Epi, class Sched, bool ALIGN_EPI = false, bool SP2 = false>
; __device__ __forceinline__ void gemm_phase(PG8_LAS unsigned char* lds, const Gemm g, const Sched& S, const Epi& E) {
;     ...
; #pragma unroll
;         for (int a = 0; a < 2; ++a)
; #pragma unroll
;             for (int b = 0; b < 2; ++b)
; #pragma unroll
;                 for (int m = 0; m < 4; ++m)
; #pragma unroll
;                     for (int n = 0; n < 2; ++n) acc[a][b][m][n] = (f32x4){0.f, 0.f, 0.f, 0.f};
;         cur = nxt; cA = nA; cB = nB; ++ui;
	s_addc_u32 s69, s81, 0
	s_mov_b32 s74, -2
	s_waitcnt lgkmcnt(0)


; #define PG8_STAGE(bufoff, gbase, voff) do { _Pragma("unroll") for (int _i = 0; _i < 2; ++_i) \
;         __builtin_amdgcn_global_load_lds((const unsigned*)((const char*)(gbase) + (voff)[_i]), (PG8_LAS unsigned*)(lds + (bufoff) + ldsw + _i * 8192), 16, 0, 0); } while (0)
; #define PG8_LDA(dst, b, h) do { _Pragma("unroll") for (int m = 0; m < 4; ++m) _Pragma("unroll") for (int k = 0; k < 2; ++k) dst[m][k] = *(const PG8_LAS bf16x8*)(lds + PG8_SA(b, h) + aoff + m * 2048 + k * 1024); } while (0)
; #define PG8_LDB(dst, b, h) do { _Pragma("unroll") for (int n = 0; n < 2; ++n) _Pragma("unroll") for (int k = 0; k < 2; ++k) dst[n][k] = *(const PG8_LAS bf16x8*)(lds + PG8_SB(b, h) + boff + n * 2048 + k * 1024); } while (0)
; #define PG8_MMA(ai, bj, At, Bt) do { __builtin_amdgcn_s_setprio(1); _Pragma("unroll") for (int m = 0; m < 4; ++m) _Pragma("unroll") for (int n = 0; n < 2; ++n) _Pragma("unroll") for (int k = 0; k < 2; ++k) \
;         acc[ai][bj][m][n] = __builtin_amdgcn_mfma_f32_16x16x32_bf16(Bt[n][k], At[m][k], acc[ai][bj][m][n], 0, 0, 0); __builtin_amdgcn_s_setprio(0); } while (0)
; #define PG8_WAIT_V(n) asm volatile("s_waitcnt vmcnt(" #n ")" ::: "memory")
; #define PG8_BAR __builtin_amdgcn_s_barrier()
; template <class Epi, class Sched, bool ALIGN_EPI = false, bool SP2 = false>
; __device__ __forceinline__ void gemm_phase(PG8_LAS unsigned char* lds, const Gemm g, const Sched& S, const Epi& E) {
;     ...
;         for (int t = 0; t < nt; t += 2) {
;             const bool last = (t == nt - 2);
;             const char* a1 = cA + (size_t)(t + 1) * kstep;
;             const char* a2 = last ? nA : cA + (size_t)(t + 2) * kstep; const char* b2 = last ? nB : cB + (size_t)(t + 2) * kstep;
;             const char* a3 = a2 + kstep; const char* b3 = b2 + kstep;
;             if (last && has_next) S.a_ready(nxt);
;             if constexpr (SP2) {
;             PG8_LDB(B0, 0, 0); PG8_LDB(B1, 0, 1); PG8_SCHED; PG8_LDA(At, 0, 0); PG8_STAGE(PG8_SA(1, 1), a1 + hstep, voffA);
;             PG8_WAIT_V(8); PG8_WAIT_L(0); PG8_BAR; PG8_MMA(0, 0, At, B0); PG8_MMA(0, 1, At, B1); PG8_BAR; PG8_SCHED;
;             PG8_LDA(At, 0, 1); PG8_STAGE(PG8_SB(0, 0), b2, voffB); PG8_STAGE(PG8_SB(0, 1), b2 + hstep, voffB); PG8_STAGE(PG8_SA(0, 0), a2, voffA);
;             PG8_WAIT_V(8); PG8_WAIT_L(0); PG8_BAR; PG8_MMA(1, 0, At, B0); PG8_MMA(1, 1, At, B1); PG8_BAR; PG8_SCHED;
	s_add_u32 s80, s24, 0x100
	s_addc_u32 s81, s25, 0
	s_add_i32 s76, 0, 0x10000
	s_cmp_eq_u32 s74, 28
	s_cselect_b32 s97, s21, s81
	s_cselect_b32 s96, s31, s80
	v_add_u32_e32 v130, s76, v191
	s_cselect_b32 vcc_hi, s29, s69
	s_cselect_b32 vcc_lo, s37, s68
	s_add_i32 s77, 0, 0x14000
	ds_read_b128 v[148:151], v130
	ds_read_b128 v[152:155], v130 offset:1024
	ds_read_b128 v[156:159], v130 offset:2048
	ds_read_b128 v[160:163], v130 offset:3072
	v_add_u32_e32 v130, s77, v191
	ds_read_b128 v[164:167], v130
	ds_read_b128 v[168:171], v130 offset:1024
	ds_read_b128 v[172:175], v130 offset:2048
	ds_read_b128 v[176:179], v130 offset:3072
	v_lshl_add_u64 v[130:131], s[24:25], 0, v[144:145]
	s_add_i32 m0, s23, 0xc000
	ds_read_b128 v[180:183], v193
	ds_read_b128 v[184:187], v193 offset:1024
	ds_read_b128 v[194:197], v193 offset:2048
	ds_read_b128 v[198:201], v193 offset:3072
	ds_read_b128 v[202:205], v193 offset:4096
	ds_read_b128 v[218:221], v193 offset:5120
	ds_read_b128 v[222:225], v193 offset:6144
	ds_read_b128 v[226:229], v193 offset:7168
	global_load_lds_dwordx4 v[130:131], off
	v_lshl_add_u64 v[130:131], s[24:25], 0, v[146:147]
	s_add_i32 m0, s23, 0xe000
	s_nop 0
	global_load_lds_dwordx4 v[130:131], off
	s_waitcnt vmcnt(8)
	s_waitcnt lgkmcnt(0)
	s_barrier
	s_setprio 1
	s_waitcnt lgkmcnt(0)
	v_mfma_f32_16x16x32_bf16 v[124:127], v[148:151], v[180:183], 0
	v_mfma_f32_16x16x32_bf16 v[120:123], v[156:159], v[180:183], 0
	v_mfma_f32_16x16x32_bf16 v[108:111], v[148:151], v[194:197], 0
	v_mfma_f32_16x16x32_bf16 v[104:107], v[156:159], v[194:197], 0
	v_mfma_f32_16x16x32_bf16 v[92:95], v[148:151], v[202:205], 0
	v_mfma_f32_16x16x32_bf16 v[88:91], v[156:159], v[202:205], 0
	v_mfma_f32_16x16x32_bf16 v[76:79], v[148:151], v[222:225], 0
	v_mfma_f32_16x16x32_bf16 v[72:75], v[156:159], v[222:225], 0
	v_mfma_f32_16x16x32_bf16 v[124:127], v[152:155], v[184:187], v[124:127]
	v_mfma_f32_16x16x32_bf16 v[120:123], v[160:163], v[184:187], v[120:123]
	v_mfma_f32_16x16x32_bf16 v[108:111], v[152:155], v[198:201], v[108:111]
	v_mfma_f32_16x16x32_bf16 v[104:107], v[160:163], v[198:201], v[104:107]
	v_mfma_f32_16x16x32_bf16 v[92:95], v[152:155], v[218:221], v[92:95]
	v_mfma_f32_16x16x32_bf16 v[88:91], v[160:163], v[218:221], v[88:91]
	v_mfma_f32_16x16x32_bf16 v[76:79], v[152:155], v[226:229], v[76:79]
	v_mfma_f32_16x16x32_bf16 v[72:75], v[160:163], v[226:229], v[72:75]
	s_setprio 0
	s_setprio 1
	v_mfma_f32_16x16x32_bf16 v[116:119], v[164:167], v[180:183], 0
	v_mfma_f32_16x16x32_bf16 v[112:115], v[172:175], v[180:183], 0
	v_mfma_f32_16x16x32_bf16 v[100:103], v[164:167], v[194:197], 0
	v_mfma_f32_16x16x32_bf16 v[96:99], v[172:175], v[194:197], 0
	v_mfma_f32_16x16x32_bf16 v[84:87], v[164:167], v[202:205], 0
	v_mfma_f32_16x16x32_bf16 v[80:83], v[172:175], v[202:205], 0
	v_mfma_f32_16x16x32_bf16 v[68:71], v[164:167], v[222:225], 0
	v_mfma_f32_16x16x32_bf16 v[64:67], v[172:175], v[222:225], 0
	v_mfma_f32_16x16x32_bf16 v[116:119], v[168:171], v[184:187], v[116:119]
	v_mfma_f32_16x16x32_bf16 v[112:115], v[176:179], v[184:187], v[112:115]
	v_mfma_f32_16x16x32_bf16 v[100:103], v[168:171], v[198:201], v[100:103]
	v_mfma_f32_16x16x32_bf16 v[96:99], v[176:179], v[198:201], v[96:99]
	v_mfma_f32_16x16x32_bf16 v[84:87], v[168:171], v[218:221], v[84:87]
	v_mfma_f32_16x16x32_bf16 v[80:83], v[176:179], v[218:221], v[80:83]
	v_mfma_f32_16x16x32_bf16 v[68:71], v[168:171], v[226:229], v[68:71]
	v_mfma_f32_16x16x32_bf16 v[64:67], v[176:179], v[226:229], v[64:67]
	s_setprio 0
	s_barrier
	s_add_i32 s24, s76, s55
	v_lshl_add_u64 v[130:131], vcc, 0, v[128:129]
	s_mov_b32 m0, s24
	ds_read_b128 v[180:183], v193 offset:16384
	ds_read_b128 v[184:187], v193 offset:17408
	ds_read_b128 v[194:197], v193 offset:18432
	ds_read_b128 v[198:201], v193 offset:19456
	ds_read_b128 v[202:205], v193 offset:20480
	ds_read_b128 v[218:221], v193 offset:21504
	ds_read_b128 v[222:225], v193 offset:22528
	ds_read_b128 v[226:229], v193 offset:23552
	global_load_lds_dwordx4 v[130:131], off
	s_add_i32 m0, s24, 0x2000
	s_add_u32 s24, vcc_lo, 0x80000
	v_lshl_add_u64 v[132:133], vcc, 0, v[142:143]
	s_addc_u32 s25, vcc_hi, 0
	s_add_i32 s76, s77, s55
	global_load_lds_dwordx4 v[132:133], off
	v_lshl_add_u64 v[188:189], s[24:25], 0, v[128:129]
	s_mov_b32 m0, s76
	v_lshl_add_u64 v[206:207], s[96:97], 0, v[142:143]
	global_load_lds_dwordx4 v[188:189], off
	v_lshl_add_u64 v[188:189], s[24:25], 0, v[142:143]
	s_add_i32 m0, s76, 0x2000
	s_nop 0
	global_load_lds_dwordx4 v[188:189], off
	v_lshl_add_u64 v[188:189], s[96:97], 0, v[128:129]
	s_mov_b32 m0, s23
	s_nop 0
	global_load_lds_dwordx4 v[188:189], off
	s_mov_b32 m0, s56
	s_nop 0
	global_load_lds_dwordx4 v[206:207], off
	s_waitcnt vmcnt(8)
	s_waitcnt lgkmcnt(0)
	s_barrier
; #define PG8_STAGE(bufoff, gbase, voff) do { _Pragma("unroll") for (int _i = 0; _i < 2; ++_i) \
;         __builtin_amdgcn_global_load_lds((const unsigned*)((const char*)(gbase) + (voff)[_i]), (PG8_LAS unsigned*)(lds + (bufoff) + ldsw + _i * 8192), 16, 0, 0); } while (0)
; #define PG8_LDA(dst, b, h) do { _Pragma("unroll") for (int m = 0; m < 4; ++m) _Pragma("unroll") for (int k = 0; k < 2; ++k) dst[m][k] = *(const PG8_LAS bf16x8*)(lds + PG8_SA(b, h) + aoff + m * 2048 + k * 1024); } while (0)
; #define PG8_LDB(dst, b, h) do { _Pragma("unroll") for (int n = 0; n < 2; ++n) _Pragma("unroll") for (int k = 0; k < 2; ++k) dst[n][k] = *(const PG8_LAS bf16x8*)(lds + PG8_SB(b, h) + boff + n * 2048 + k * 1024); } while (0)
; #define PG8_MMA(ai, bj, At, Bt) do { __builtin_amdgcn_s_setprio(1); _Pragma("unroll") for (int m = 0; m < 4; ++m) _Pragma("unroll") for (int n = 0; n < 2; ++n) _Pragma("unroll") for (int k = 0; k < 2; ++k) \
;         acc[ai][bj][m][n] = __builtin_amdgcn_mfma_f32_16x16x32_bf16(Bt[n][k], At[m][k], acc[ai][bj][m][n], 0, 0, 0); __builtin_amdgcn_s_setprio(0); } while (0)
; #define PG8_WAIT_V(n) asm volatile("s_waitcnt vmcnt(" #n ")" ::: "memory")
; #define PG8_WAIT_L(n) asm volatile("s_waitcnt lgkmcnt(" #n ")" ::: "memory")
; #define PG8_BAR __builtin_amdgcn_s_barrier()
; #define PG8_SCHED __builtin_amdgcn_sched_barrier(0)
; template <class Epi, class Sched, bool ALIGN_EPI = false, bool SP2 = false>
; __device__ __forceinline__ void gemm_phase(PG8_LAS unsigned char* lds, const Gemm g, const Sched& S, const Epi& E) {
;     ...
;             PG8_WAIT_V(8); PG8_WAIT_L(0); PG8_BAR; PG8_MMA(1, 0, At, B0); PG8_MMA(1, 1, At, B1); PG8_BAR; PG8_SCHED;
;             PG8_LDB(B0, 1, 0); PG8_LDB(B1, 1, 1); PG8_SCHED; PG8_LDA(At, 1, 0); PG8_STAGE(PG8_SA(0, 1), a2 + hstep, voffA);
;             PG8_WAIT_V(8); PG8_WAIT_L(0); PG8_BAR; PG8_MMA(0, 0, At, B0); PG8_MMA(0, 1, At, B1); PG8_BAR; PG8_SCHED;
	s_setprio 1
	s_waitcnt lgkmcnt(0)
	v_mfma_f32_16x16x32_bf16 v[60:63], v[148:151], v[180:183], 0
	v_mfma_f32_16x16x32_bf16 v[56:59], v[156:159], v[180:183], 0
	v_mfma_f32_16x16x32_bf16 v[44:47], v[148:151], v[194:197], 0
	v_mfma_f32_16x16x32_bf16 v[40:43], v[156:159], v[194:197], 0
	v_mfma_f32_16x16x32_bf16 v[28:31], v[148:151], v[202:205], 0
	v_mfma_f32_16x16x32_bf16 v[24:27], v[156:159], v[202:205], 0
	v_mfma_f32_16x16x32_bf16 v[12:15], v[148:151], v[222:225], 0
	v_mfma_f32_16x16x32_bf16 v[8:11], v[156:159], v[222:225], 0
	v_mfma_f32_16x16x32_bf16 v[60:63], v[152:155], v[184:187], v[60:63]
	v_mfma_f32_16x16x32_bf16 v[56:59], v[160:163], v[184:187], v[56:59]
	v_mfma_f32_16x16x32_bf16 v[44:47], v[152:155], v[198:201], v[44:47]
	v_mfma_f32_16x16x32_bf16 v[40:43], v[160:163], v[198:201], v[40:43]
	v_mfma_f32_16x16x32_bf16 v[28:31], v[152:155], v[218:221], v[28:31]
	v_mfma_f32_16x16x32_bf16 v[24:27], v[160:163], v[218:221], v[24:27]
	v_mfma_f32_16x16x32_bf16 v[12:15], v[152:155], v[226:229], v[12:15]
	v_mfma_f32_16x16x32_bf16 v[8:11], v[160:163], v[226:229], v[8:11]
	s_setprio 0
	s_setprio 1
	v_mfma_f32_16x16x32_bf16 v[52:55], v[164:167], v[180:183], 0
	v_mfma_f32_16x16x32_bf16 v[48:51], v[172:175], v[180:183], 0
	v_mfma_f32_16x16x32_bf16 v[36:39], v[164:167], v[194:197], 0
	v_mfma_f32_16x16x32_bf16 v[32:35], v[172:175], v[194:197], 0
	v_mfma_f32_16x16x32_bf16 v[20:23], v[164:167], v[202:205], 0
	v_mfma_f32_16x16x32_bf16 v[16:19], v[172:175], v[202:205], 0
	v_mfma_f32_16x16x32_bf16 v[4:7], v[164:167], v[222:225], 0
	v_mfma_f32_16x16x32_bf16 v[0:3], v[172:175], v[222:225], 0
	v_mfma_f32_16x16x32_bf16 v[52:55], v[168:171], v[184:187], v[52:55]
	v_mfma_f32_16x16x32_bf16 v[48:51], v[176:179], v[184:187], v[48:51]
	v_mfma_f32_16x16x32_bf16 v[36:39], v[168:171], v[198:201], v[36:39]
	v_mfma_f32_16x16x32_bf16 v[32:35], v[176:179], v[198:201], v[32:35]
	v_mfma_f32_16x16x32_bf16 v[20:23], v[168:171], v[218:221], v[20:23]
	v_mfma_f32_16x16x32_bf16 v[16:19], v[176:179], v[218:221], v[16:19]
	v_mfma_f32_16x16x32_bf16 v[4:7], v[168:171], v[226:229], v[4:7]
	v_mfma_f32_16x16x32_bf16 v[0:3], v[176:179], v[226:229], v[0:3]
	s_setprio 0
	s_barrier
	s_add_i32 s76, 0, 0x18000
	v_add_u32_e32 v134, s76, v191
	s_add_i32 s77, 0, 0x1c000
	ds_read_b128 v[148:151], v134
	ds_read_b128 v[152:155], v134 offset:1024
	ds_read_b128 v[156:159], v134 offset:2048
	ds_read_b128 v[160:163], v134 offset:3072
	v_add_u32_e32 v134, s77, v191
	ds_read_b128 v[164:167], v134
	ds_read_b128 v[168:171], v134 offset:1024
	ds_read_b128 v[172:175], v134 offset:2048
	ds_read_b128 v[176:179], v134 offset:3072
	s_add_u32 s24, s96, 0x80000
	s_addc_u32 s25, s97, 0
	s_mov_b32 m0, s57
	v_lshl_add_u64 v[230:231], s[24:25], 0, v[128:129]
	ds_read_b128 v[180:183], v193 offset:32768
	ds_read_b128 v[184:187], v193 offset:33792
	ds_read_b128 v[194:197], v193 offset:34816
	ds_read_b128 v[198:201], v193 offset:35840
	ds_read_b128 v[202:205], v193 offset:36864
	ds_read_b128 v[218:221], v193 offset:37888
	ds_read_b128 v[222:225], v193 offset:38912
	ds_read_b128 v[226:229], v193 offset:39936
	global_load_lds_dwordx4 v[230:231], off
	v_lshl_add_u64 v[230:231], s[24:25], 0, v[142:143]
	s_mov_b32 m0, s58
	s_nop 0
	global_load_lds_dwordx4 v[230:231], off
	s_waitcnt vmcnt(8)
	s_waitcnt lgkmcnt(0)
	s_barrier
	s_setprio 1
	s_waitcnt lgkmcnt(0)
	v_mfma_f32_16x16x32_bf16 v[124:127], v[148:151], v[180:183], v[124:127]
	v_mfma_f32_16x16x32_bf16 v[120:123], v[156:159], v[180:183], v[120:123]
	v_mfma_f32_16x16x32_bf16 v[108:111], v[148:151], v[194:197], v[108:111]
	v_mfma_f32_16x16x32_bf16 v[104:107], v[156:159], v[194:197], v[104:107]
	v_mfma_f32_16x16x32_bf16 v[92:95], v[148:151], v[202:205], v[92:95]
	v_mfma_f32_16x16x32_bf16 v[88:91], v[156:159], v[202:205], v[88:91]
	v_mfma_f32_16x16x32_bf16 v[76:79], v[148:151], v[222:225], v[76:79]
	v_mfma_f32_16x16x32_bf16 v[72:75], v[156:159], v[222:225], v[72:75]
	v_mfma_f32_16x16x32_bf16 v[124:127], v[152:155], v[184:187], v[124:127]
	v_mfma_f32_16x16x32_bf16 v[120:123], v[160:163], v[184:187], v[120:123]
	v_mfma_f32_16x16x32_bf16 v[108:111], v[152:155], v[198:201], v[108:111]
	v_mfma_f32_16x16x32_bf16 v[104:107], v[160:163], v[198:201], v[104:107]
	v_mfma_f32_16x16x32_bf16 v[92:95], v[152:155], v[218:221], v[92:95]
	v_mfma_f32_16x16x32_bf16 v[88:91], v[160:163], v[218:221], v[88:91]
	v_mfma_f32_16x16x32_bf16 v[76:79], v[152:155], v[226:229], v[76:79]
	v_mfma_f32_16x16x32_bf16 v[72:75], v[160:163], v[226:229], v[72:75]
	s_setprio 0
	s_setprio 1
	v_mfma_f32_16x16x32_bf16 v[116:119], v[164:167], v[180:183], v[116:119]
	v_mfma_f32_16x16x32_bf16 v[112:115], v[172:175], v[180:183], v[112:115]
	v_mfma_f32_16x16x32_bf16 v[100:103], v[164:167], v[194:197], v[100:103]
	v_mfma_f32_16x16x32_bf16 v[96:99], v[172:175], v[194:197], v[96:99]
	v_mfma_f32_16x16x32_bf16 v[84:87], v[164:167], v[202:205], v[84:87]
	v_mfma_f32_16x16x32_bf16 v[80:83], v[172:175], v[202:205], v[80:83]
	v_mfma_f32_16x16x32_bf16 v[68:71], v[164:167], v[222:225], v[68:71]
	v_mfma_f32_16x16x32_bf16 v[64:67], v[172:175], v[222:225], v[64:67]
	v_mfma_f32_16x16x32_bf16 v[116:119], v[168:171], v[184:187], v[116:119]
	v_mfma_f32_16x16x32_bf16 v[112:115], v[176:179], v[184:187], v[112:115]
	v_mfma_f32_16x16x32_bf16 v[100:103], v[168:171], v[198:201], v[100:103]
	v_mfma_f32_16x16x32_bf16 v[96:99], v[176:179], v[198:201], v[96:99]
	v_mfma_f32_16x16x32_bf16 v[84:87], v[168:171], v[218:221], v[84:87]
	v_mfma_f32_16x16x32_bf16 v[80:83], v[176:179], v[218:221], v[80:83]
	v_mfma_f32_16x16x32_bf16 v[68:71], v[168:171], v[226:229], v[68:71]
	v_mfma_f32_16x16x32_bf16 v[64:67], v[176:179], v[226:229], v[64:67]
	s_setprio 0
	s_barrier
; #define PG8_STAGE(bufoff, gbase, voff) do { _Pragma("unroll") for (int _i = 0; _i < 2; ++_i) \
;         __builtin_amdgcn_global_load_lds((const unsigned*)((const char*)(gbase) + (voff)[_i]), (PG8_LAS unsigned*)(lds + (bufoff) + ldsw + _i * 8192), 16, 0, 0); } while (0)
; #define PG8_LDA(dst, b, h) do { _Pragma("unroll") for (int m = 0; m < 4; ++m) _Pragma("unroll") for (int k = 0; k < 2; ++k) dst[m][k] = *(const PG8_LAS bf16x8*)(lds + PG8_SA(b, h) + aoff + m * 2048 + k * 1024); } while (0)
; #define PG8_MMA(ai, bj, At, Bt) do { __builtin_amdgcn_s_setprio(1); _Pragma("unroll") for (int m = 0; m < 4; ++m) _Pragma("unroll") for (int n = 0; n < 2; ++n) _Pragma("unroll") for (int k = 0; k < 2; ++k) \
;         acc[ai][bj][m][n] = __builtin_amdgcn_mfma_f32_16x16x32_bf16(Bt[n][k], At[m][k], acc[ai][bj][m][n], 0, 0, 0); __builtin_amdgcn_s_setprio(0); } while (0)
; #define PG8_WAIT_V(n) asm volatile("s_waitcnt vmcnt(" #n ")" ::: "memory")
; #define PG8_WAIT_L(n) asm volatile("s_waitcnt lgkmcnt(" #n ")" ::: "memory")
; #define PG8_BAR __builtin_amdgcn_s_barrier()
; #define PG8_SCHED __builtin_amdgcn_sched_barrier(0)
; template <class Epi, class Sched, bool ALIGN_EPI = false, bool SP2 = false>
; __device__ __forceinline__ void gemm_phase(PG8_LAS unsigned char* lds, const Gemm g, const Sched& S, const Epi& E) {
;     ...
;         for (int t = 0; t < nt; t += 2) {
;     ...
;             PG8_LDA(At, 1, 1); PG8_STAGE(PG8_SB(1, 0), b3, voffB); PG8_STAGE(PG8_SB(1, 1), b3 + hstep, voffB); PG8_STAGE(PG8_SA(1, 0), a3, voffA);
;             PG8_WAIT_V(8); PG8_WAIT_L(0); PG8_BAR; PG8_MMA(1, 0, At, B0); PG8_MMA(1, 1, At, B1); PG8_BAR; PG8_SCHED;
	s_add_i32 s24, s76, s55
	v_lshl_add_u64 v[130:131], v[130:131], 0, s[78:79]
	s_mov_b32 m0, s24
	ds_read_b128 v[180:183], v193 offset:49152
	ds_read_b128 v[184:187], v193 offset:50176
	ds_read_b128 v[194:197], v193 offset:51200
	ds_read_b128 v[198:201], v193 offset:52224
	ds_read_b128 v[202:205], v193 offset:53248
	ds_read_b128 v[218:221], v193 offset:54272
	ds_read_b128 v[222:225], v193 offset:55296
	ds_read_b128 v[226:229], v193 offset:56320
	global_load_lds_dwordx4 v[130:131], off
	s_add_i32 m0, s24, 0x2000
	s_add_u32 s24, vcc_lo, 0x80080
	v_lshl_add_u64 v[130:131], v[132:133], 0, s[78:79]
	s_addc_u32 s25, vcc_hi, 0
	s_add_i32 s76, s77, s55
	global_load_lds_dwordx4 v[130:131], off
	v_lshl_add_u64 v[130:131], s[24:25], 0, v[128:129]
	s_mov_b32 m0, s76
	s_nop 0
	global_load_lds_dwordx4 v[130:131], off
	v_lshl_add_u64 v[130:131], s[24:25], 0, v[142:143]
	s_add_i32 m0, s76, 0x2000
	s_nop 0
	global_load_lds_dwordx4 v[130:131], off
	v_lshl_add_u64 v[130:131], v[188:189], 0, s[78:79]
	s_mov_b32 m0, s60
	s_nop 0
	global_load_lds_dwordx4 v[130:131], off
	v_lshl_add_u64 v[130:131], v[206:207], 0, s[78:79]
	s_mov_b32 m0, s61
	s_nop 0
	global_load_lds_dwordx4 v[130:131], off
	s_waitcnt vmcnt(8)
	s_waitcnt lgkmcnt(0)
	s_barrier
	s_setprio 1
	s_waitcnt lgkmcnt(0)
	v_mfma_f32_16x16x32_bf16 v[60:63], v[148:151], v[180:183], v[60:63]
	v_mfma_f32_16x16x32_bf16 v[56:59], v[156:159], v[180:183], v[56:59]
	v_mfma_f32_16x16x32_bf16 v[44:47], v[148:151], v[194:197], v[44:47]
	v_mfma_f32_16x16x32_bf16 v[40:43], v[156:159], v[194:197], v[40:43]
	v_mfma_f32_16x16x32_bf16 v[28:31], v[148:151], v[202:205], v[28:31]
	v_mfma_f32_16x16x32_bf16 v[24:27], v[156:159], v[202:205], v[24:27]
	v_mfma_f32_16x16x32_bf16 v[12:15], v[148:151], v[222:225], v[12:15]
	v_mfma_f32_16x16x32_bf16 v[8:11], v[156:159], v[222:225], v[8:11]
	v_mfma_f32_16x16x32_bf16 v[60:63], v[152:155], v[184:187], v[60:63]
	v_mfma_f32_16x16x32_bf16 v[56:59], v[160:163], v[184:187], v[56:59]
	v_mfma_f32_16x16x32_bf16 v[44:47], v[152:155], v[198:201], v[44:47]
	v_mfma_f32_16x16x32_bf16 v[40:43], v[160:163], v[198:201], v[40:43]
	v_mfma_f32_16x16x32_bf16 v[28:31], v[152:155], v[218:221], v[28:31]
	v_mfma_f32_16x16x32_bf16 v[24:27], v[160:163], v[218:221], v[24:27]
	v_mfma_f32_16x16x32_bf16 v[12:15], v[152:155], v[226:229], v[12:15]
	v_mfma_f32_16x16x32_bf16 v[8:11], v[160:163], v[226:229], v[8:11]
	s_setprio 0
	s_setprio 1
	v_mfma_f32_16x16x32_bf16 v[52:55], v[164:167], v[180:183], v[52:55]
	v_mfma_f32_16x16x32_bf16 v[48:51], v[172:175], v[180:183], v[48:51]
	v_mfma_f32_16x16x32_bf16 v[36:39], v[164:167], v[194:197], v[36:39]
	v_mfma_f32_16x16x32_bf16 v[32:35], v[172:175], v[194:197], v[32:35]
	v_mfma_f32_16x16x32_bf16 v[20:23], v[164:167], v[202:205], v[20:23]
	v_mfma_f32_16x16x32_bf16 v[16:19], v[172:175], v[202:205], v[16:19]
	v_mfma_f32_16x16x32_bf16 v[4:7], v[164:167], v[222:225], v[4:7]
	v_mfma_f32_16x16x32_bf16 v[0:3], v[172:175], v[222:225], v[0:3]
	v_mfma_f32_16x16x32_bf16 v[52:55], v[168:171], v[184:187], v[52:55]
	v_mfma_f32_16x16x32_bf16 v[48:51], v[176:179], v[184:187], v[48:51]
	v_mfma_f32_16x16x32_bf16 v[36:39], v[168:171], v[198:201], v[36:39]
	v_mfma_f32_16x16x32_bf16 v[32:35], v[176:179], v[198:201], v[32:35]
	v_mfma_f32_16x16x32_bf16 v[20:23], v[168:171], v[218:221], v[20:23]
	v_mfma_f32_16x16x32_bf16 v[16:19], v[176:179], v[218:221], v[16:19]
	v_mfma_f32_16x16x32_bf16 v[4:7], v[168:171], v[226:229], v[4:7]
	v_mfma_f32_16x16x32_bf16 v[0:3], v[176:179], v[226:229], v[0:3]
	s_setprio 0
	s_barrier
	s_add_i32 s74, s74, 2
	s_add_u32 s68, s68, 0x100
	s_addc_u32 s69, s69, 0
	s_cmp_gt_u32 s74, 29
	s_mov_b64 s[24:25], s[80:81]

; template <class Epi, class Sched, bool ALIGN_EPI = false, bool SP2 = false>
; __device__ __forceinline__ void gemm_phase(PG8_LAS unsigned char* lds, const Gemm g, const Sched& S, const Epi& E) {
;     ...
;         const bool has_next = S.next(ui + 1, nxt);
;         const char* nA = has_next ? (const char*)g.A + (size_t)nxt.pm * tstep : cA; const char* nB = has_next ? (const char*)g.Bt + (size_t)nxt.pn * tstep : cB;
;         for (int t = 0; t < nt; t += 2) {
;             const bool last = (t == nt - 2);
;             const char* a1 = cA + (size_t)(t + 1) * kstep;
;             const char* a2 = last ? nA : cA + (size_t)(t + 2) * kstep; const char* b2 = last ? nB : cB + (size_t)(t + 2) * kstep;
;             const char* a3 = a2 + kstep; const char* b3 = b2 + kstep;
;     ...
; #pragma unroll
;         for (int a = 0; a < 2; ++a)
; #pragma unroll
;             for (int b = 0; b < 2; ++b)
; #pragma unroll
;                 for (int m = 0; m < 4; ++m)
; #pragma unroll
;                     for (int n = 0; n < 2; ++n) acc[a][b][m][n] = (f32x4){0.f, 0.f, 0.f, 0.f};
;         cur = nxt; cA = nA; cB = nB; ++ui;
.LBB0_954:
	s_ashr_i32 s23, s22, 31
	s_lshl_b64 s[24:25], s[22:23], 20
	s_add_u32 s24, s38, s24
	s_addc_u32 s25, s39, s25
	s_and_b64 s[26:27], s[40:41], exec
	s_cselect_b32 s23, s25, s31
	s_cselect_b32 s60, s24, s30
	s_ashr_i32 s21, s20, 31
	s_lshl_b64 s[26:27], s[20:21], 20
	s_add_u32 s26, s54, s26
	s_addc_u32 s27, s55, s27
	s_and_b64 s[42:43], s[40:41], exec
	s_cselect_b32 s21, s27, s35
	s_cselect_b32 s61, s26, s34
	s_add_u32 s30, s30, 0x80080
	s_addc_u32 s31, s31, 0
	s_add_u32 s62, s34, 0x100

; template <class Epi, class Sched, bool ALIGN_EPI = false, bool SP2 = false>
; __device__ __forceinline__ void gemm_phase(PG8_LAS unsigned char* lds, const Gemm g, const Sched& S, const Epi& E) {
;     ...
; #pragma unroll
;         for (int a = 0; a < 2; ++a)
; #pragma unroll
;             for (int b = 0; b < 2; ++b)
; #pragma unroll
;                 for (int m = 0; m < 4; ++m)
; #pragma unroll
;                     for (int n = 0; n < 2; ++n) acc[a][b][m][n] = (f32x4){0.f, 0.f, 0.f, 0.f};
;         cur = nxt; cA = nA; cB = nB; ++ui;
	s_addc_u32 s68, s35, 0
	s_mov_b32 s69, -2


; #define PG8_STAGE(bufoff, gbase, voff) do { _Pragma("unroll") for (int _i = 0; _i < 2; ++_i) \
;         __builtin_amdgcn_global_load_lds((const unsigned*)((const char*)(gbase) + (voff)[_i]), (PG8_LAS unsigned*)(lds + (bufoff) + ldsw + _i * 8192), 16, 0, 0); } while (0)
; #define PG8_LDA(dst, b, h) do { _Pragma("unroll") for (int m = 0; m < 4; ++m) _Pragma("unroll") for (int k = 0; k < 2; ++k) dst[m][k] = *(const PG8_LAS bf16x8*)(lds + PG8_SA(b, h) + aoff + m * 2048 + k * 1024); } while (0)
; #define PG8_LDB(dst, b, h) do { _Pragma("unroll") for (int n = 0; n < 2; ++n) _Pragma("unroll") for (int k = 0; k < 2; ++k) dst[n][k] = *(const PG8_LAS bf16x8*)(lds + PG8_SB(b, h) + boff + n * 2048 + k * 1024); } while (0)
; #define PG8_MMA(ai, bj, At, Bt) do { __builtin_amdgcn_s_setprio(1); _Pragma("unroll") for (int m = 0; m < 4; ++m) _Pragma("unroll") for (int n = 0; n < 2; ++n) _Pragma("unroll") for (int k = 0; k < 2; ++k) \
;         acc[ai][bj][m][n] = __builtin_amdgcn_mfma_f32_16x16x32_bf16(Bt[n][k], At[m][k], acc[ai][bj][m][n], 0, 0, 0); __builtin_amdgcn_s_setprio(0); } while (0)
; #define PG8_WAIT_V(n) asm volatile("s_waitcnt vmcnt(" #n ")" ::: "memory")
; #define PG8_BAR __builtin_amdgcn_s_barrier()
; template <class Epi, class Sched, bool ALIGN_EPI = false, bool SP2 = false>
; __device__ __forceinline__ void gemm_phase(PG8_LAS unsigned char* lds, const Gemm g, const Sched& S, const Epi& E) {
;     ...
;         for (int t = 0; t < nt; t += 2) {
;             const bool last = (t == nt - 2);
;             const char* a1 = cA + (size_t)(t + 1) * kstep;
;             const char* a2 = last ? nA : cA + (size_t)(t + 2) * kstep; const char* b2 = last ? nB : cB + (size_t)(t + 2) * kstep;
;             const char* a3 = a2 + kstep; const char* b3 = b2 + kstep;
;             if (last && has_next) S.a_ready(nxt);
;             if constexpr (SP2) {
;             PG8_LDB(B0, 0, 0); PG8_LDB(B1, 0, 1); PG8_SCHED; PG8_LDA(At, 0, 0); PG8_STAGE(PG8_SA(1, 1), a1 + hstep, voffA);
;             PG8_WAIT_V(8); PG8_WAIT_L(0); PG8_BAR; PG8_MMA(0, 0, At, B0); PG8_MMA(0, 1, At, B1); PG8_BAR; PG8_SCHED;
;             PG8_LDA(At, 0, 1); PG8_STAGE(PG8_SB(0, 0), b2, voffB); PG8_STAGE(PG8_SB(0, 1), b2 + hstep, voffB); PG8_STAGE(PG8_SA(0, 0), a2, voffA);
;             PG8_WAIT_V(8); PG8_WAIT_L(0); PG8_BAR; PG8_MMA(1, 0, At, B0); PG8_MMA(1, 1, At, B1); PG8_BAR; PG8_SCHED;
	s_add_u32 s34, s30, 0xfff80080
	s_addc_u32 s35, s31, -1
	s_add_i32 s76, 0, 0x10000
	s_cmp_eq_u32 s69, 28
	s_cselect_b32 s43, s23, s35
	s_cselect_b32 s42, s60, s34
	v_add_u32_e32 v130, s76, v159
	s_cselect_b32 s35, s21, s68
	s_cselect_b32 s34, s61, s62
	s_add_i32 vcc_lo, 0, 0x14000
	ds_read_b128 v[154:157], v130
	ds_read_b128 v[164:167], v130 offset:1024
	ds_read_b128 v[168:171], v130 offset:2048
	ds_read_b128 v[172:175], v130 offset:3072
	v_add_u32_e32 v130, vcc_lo, v159
	ds_read_b128 v[176:179], v130
	ds_read_b128 v[180:183], v130 offset:1024
	ds_read_b128 v[184:187], v130 offset:2048
	ds_read_b128 v[188:191], v130 offset:3072
	v_lshl_add_u64 v[130:131], s[30:31], 0, v[148:149]
	s_add_i32 m0, s56, 0xc000
	ds_read_b128 v[192:195], v163
	ds_read_b128 v[196:199], v163 offset:1024
	ds_read_b128 v[200:203], v163 offset:2048
	ds_read_b128 v[204:207], v163 offset:3072
	ds_read_b128 v[218:221], v163 offset:4096
	ds_read_b128 v[222:225], v163 offset:5120
	ds_read_b128 v[226:229], v163 offset:6144
	ds_read_b128 v[230:233], v163 offset:7168
	global_load_lds_dwordx4 v[130:131], off
	v_lshl_add_u64 v[130:131], s[30:31], 0, v[150:151]
	s_add_i32 m0, s56, 0xe000
	s_nop 0
	global_load_lds_dwordx4 v[130:131], off
	s_waitcnt vmcnt(8)
	s_waitcnt lgkmcnt(0)
	s_barrier
	s_setprio 1
	s_waitcnt lgkmcnt(0)
	v_mfma_f32_16x16x32_bf16 v[124:127], v[154:157], v[192:195], 0
	v_mfma_f32_16x16x32_bf16 v[120:123], v[168:171], v[192:195], 0
	v_mfma_f32_16x16x32_bf16 v[108:111], v[154:157], v[200:203], 0
	v_mfma_f32_16x16x32_bf16 v[104:107], v[168:171], v[200:203], 0
	v_mfma_f32_16x16x32_bf16 v[92:95], v[154:157], v[218:221], 0
	v_mfma_f32_16x16x32_bf16 v[88:91], v[168:171], v[218:221], 0
	v_mfma_f32_16x16x32_bf16 v[76:79], v[154:157], v[226:229], 0
	v_mfma_f32_16x16x32_bf16 v[72:75], v[168:171], v[226:229], 0
	v_mfma_f32_16x16x32_bf16 v[124:127], v[164:167], v[196:199], v[124:127]
	v_mfma_f32_16x16x32_bf16 v[120:123], v[172:175], v[196:199], v[120:123]
	v_mfma_f32_16x16x32_bf16 v[108:111], v[164:167], v[204:207], v[108:111]
	v_mfma_f32_16x16x32_bf16 v[104:107], v[172:175], v[204:207], v[104:107]
	v_mfma_f32_16x16x32_bf16 v[92:95], v[164:167], v[222:225], v[92:95]
	v_mfma_f32_16x16x32_bf16 v[88:91], v[172:175], v[222:225], v[88:91]
	v_mfma_f32_16x16x32_bf16 v[76:79], v[164:167], v[230:233], v[76:79]
	v_mfma_f32_16x16x32_bf16 v[72:75], v[172:175], v[230:233], v[72:75]
	s_setprio 0
	s_setprio 1
	v_mfma_f32_16x16x32_bf16 v[116:119], v[176:179], v[192:195], 0
	v_mfma_f32_16x16x32_bf16 v[112:115], v[184:187], v[192:195], 0
	v_mfma_f32_16x16x32_bf16 v[100:103], v[176:179], v[200:203], 0
	v_mfma_f32_16x16x32_bf16 v[96:99], v[184:187], v[200:203], 0
	v_mfma_f32_16x16x32_bf16 v[84:87], v[176:179], v[218:221], 0
	v_mfma_f32_16x16x32_bf16 v[80:83], v[184:187], v[218:221], 0
	v_mfma_f32_16x16x32_bf16 v[68:71], v[176:179], v[226:229], 0
	v_mfma_f32_16x16x32_bf16 v[64:67], v[184:187], v[226:229], 0
	v_mfma_f32_16x16x32_bf16 v[116:119], v[180:183], v[196:199], v[116:119]
	v_mfma_f32_16x16x32_bf16 v[112:115], v[188:191], v[196:199], v[112:115]
	v_mfma_f32_16x16x32_bf16 v[100:103], v[180:183], v[204:207], v[100:103]
	v_mfma_f32_16x16x32_bf16 v[96:99], v[188:191], v[204:207], v[96:99]
	v_mfma_f32_16x16x32_bf16 v[84:87], v[180:183], v[222:225], v[84:87]
	v_mfma_f32_16x16x32_bf16 v[80:83], v[188:191], v[222:225], v[80:83]
	v_mfma_f32_16x16x32_bf16 v[68:71], v[180:183], v[230:233], v[68:71]
	v_mfma_f32_16x16x32_bf16 v[64:67], v[188:191], v[230:233], v[64:67]
	s_setprio 0
	s_barrier
	s_add_i32 s76, s76, s74
	v_lshl_add_u64 v[130:131], s[34:35], 0, v[128:129]
	s_mov_b32 m0, s76
	ds_read_b128 v[192:195], v163 offset:16384
	ds_read_b128 v[196:199], v163 offset:17408
	ds_read_b128 v[200:203], v163 offset:18432
	ds_read_b128 v[204:207], v163 offset:19456
	ds_read_b128 v[218:221], v163 offset:20480
	ds_read_b128 v[222:225], v163 offset:21504
	ds_read_b128 v[226:229], v163 offset:22528
	ds_read_b128 v[230:233], v163 offset:23552
	global_load_lds_dwordx4 v[130:131], off
	s_add_i32 m0, s76, 0x2000
	s_add_u32 s76, s34, 0x80000
	v_lshl_add_u64 v[132:133], s[34:35], 0, v[142:143]
	s_addc_u32 s77, s35, 0
	s_add_i32 vcc_lo, vcc_lo, s74
	global_load_lds_dwordx4 v[132:133], off
	v_lshl_add_u64 v[234:235], s[76:77], 0, v[128:129]
	s_mov_b32 m0, vcc_lo
	v_lshl_add_u64 v[236:237], s[42:43], 0, v[144:145]
	global_load_lds_dwordx4 v[234:235], off
	v_lshl_add_u64 v[234:235], s[76:77], 0, v[142:143]
	s_add_i32 m0, vcc_lo, 0x2000
	s_nop 0
	global_load_lds_dwordx4 v[234:235], off
	v_lshl_add_u64 v[234:235], s[42:43], 0, v[146:147]
	s_mov_b32 m0, s56
	s_nop 0
	global_load_lds_dwordx4 v[234:235], off
	s_mov_b32 m0, s57
	s_nop 0
	global_load_lds_dwordx4 v[236:237], off
	s_waitcnt vmcnt(8)
	s_waitcnt lgkmcnt(0)
	s_barrier
; #define PG8_STAGE(bufoff, gbase, voff) do { _Pragma("unroll") for (int _i = 0; _i < 2; ++_i) \
;         __builtin_amdgcn_global_load_lds((const unsigned*)((const char*)(gbase) + (voff)[_i]), (PG8_LAS unsigned*)(lds + (bufoff) + ldsw + _i * 8192), 16, 0, 0); } while (0)
; #define PG8_LDA(dst, b, h) do { _Pragma("unroll") for (int m = 0; m < 4; ++m) _Pragma("unroll") for (int k = 0; k < 2; ++k) dst[m][k] = *(const PG8_LAS bf16x8*)(lds + PG8_SA(b, h) + aoff + m * 2048 + k * 1024); } while (0)
; #define PG8_LDB(dst, b, h) do { _Pragma("unroll") for (int n = 0; n < 2; ++n) _Pragma("unroll") for (int k = 0; k < 2; ++k) dst[n][k] = *(const PG8_LAS bf16x8*)(lds + PG8_SB(b, h) + boff + n * 2048 + k * 1024); } while (0)
; #define PG8_MMA(ai, bj, At, Bt) do { __builtin_amdgcn_s_setprio(1); _Pragma("unroll") for (int m = 0; m < 4; ++m) _Pragma("unroll") for (int n = 0; n < 2; ++n) _Pragma("unroll") for (int k = 0; k < 2; ++k) \
;         acc[ai][bj][m][n] = __builtin_amdgcn_mfma_f32_16x16x32_bf16(Bt[n][k], At[m][k], acc[ai][bj][m][n], 0, 0, 0); __builtin_amdgcn_s_setprio(0); } while (0)
; #define PG8_WAIT_V(n) asm volatile("s_waitcnt vmcnt(" #n ")" ::: "memory")
; #define PG8_WAIT_L(n) asm volatile("s_waitcnt lgkmcnt(" #n ")" ::: "memory")
; #define PG8_BAR __builtin_amdgcn_s_barrier()
; #define PG8_SCHED __builtin_amdgcn_sched_barrier(0)
; template <class Epi, class Sched, bool ALIGN_EPI = false, bool SP2 = false>
; __device__ __forceinline__ void gemm_phase(PG8_LAS unsigned char* lds, const Gemm g, const Sched& S, const Epi& E) {
;     ...
;             PG8_WAIT_V(8); PG8_WAIT_L(0); PG8_BAR; PG8_MMA(1, 0, At, B0); PG8_MMA(1, 1, At, B1); PG8_BAR; PG8_SCHED;
;             PG8_LDB(B0, 1, 0); PG8_LDB(B1, 1, 1); PG8_SCHED; PG8_LDA(At, 1, 0); PG8_STAGE(PG8_SA(0, 1), a2 + hstep, voffA);
;             PG8_WAIT_V(8); PG8_WAIT_L(0); PG8_BAR; PG8_MMA(0, 0, At, B0); PG8_MMA(0, 1, At, B1); PG8_BAR; PG8_SCHED;
	s_setprio 1
	s_waitcnt lgkmcnt(0)
	v_mfma_f32_16x16x32_bf16 v[60:63], v[154:157], v[192:195], 0
	v_mfma_f32_16x16x32_bf16 v[56:59], v[168:171], v[192:195], 0
	v_mfma_f32_16x16x32_bf16 v[44:47], v[154:157], v[200:203], 0
	v_mfma_f32_16x16x32_bf16 v[40:43], v[168:171], v[200:203], 0
	v_mfma_f32_16x16x32_bf16 v[28:31], v[154:157], v[218:221], 0
	v_mfma_f32_16x16x32_bf16 v[24:27], v[168:171], v[218:221], 0
	v_mfma_f32_16x16x32_bf16 v[12:15], v[154:157], v[226:229], 0
	v_mfma_f32_16x16x32_bf16 v[8:11], v[168:171], v[226:229], 0
	v_mfma_f32_16x16x32_bf16 v[60:63], v[164:167], v[196:199], v[60:63]
	v_mfma_f32_16x16x32_bf16 v[56:59], v[172:175], v[196:199], v[56:59]
	v_mfma_f32_16x16x32_bf16 v[44:47], v[164:167], v[204:207], v[44:47]
	v_mfma_f32_16x16x32_bf16 v[40:43], v[172:175], v[204:207], v[40:43]
	v_mfma_f32_16x16x32_bf16 v[28:31], v[164:167], v[222:225], v[28:31]
	v_mfma_f32_16x16x32_bf16 v[24:27], v[172:175], v[222:225], v[24:27]
	v_mfma_f32_16x16x32_bf16 v[12:15], v[164:167], v[230:233], v[12:15]
	v_mfma_f32_16x16x32_bf16 v[8:11], v[172:175], v[230:233], v[8:11]
	s_setprio 0
	s_setprio 1
	v_mfma_f32_16x16x32_bf16 v[52:55], v[176:179], v[192:195], 0
	v_mfma_f32_16x16x32_bf16 v[48:51], v[184:187], v[192:195], 0
	v_mfma_f32_16x16x32_bf16 v[36:39], v[176:179], v[200:203], 0
	v_mfma_f32_16x16x32_bf16 v[32:35], v[184:187], v[200:203], 0
	v_mfma_f32_16x16x32_bf16 v[20:23], v[176:179], v[218:221], 0
	v_mfma_f32_16x16x32_bf16 v[16:19], v[184:187], v[218:221], 0
	v_mfma_f32_16x16x32_bf16 v[4:7], v[176:179], v[226:229], 0
	v_mfma_f32_16x16x32_bf16 v[0:3], v[184:187], v[226:229], 0
	v_mfma_f32_16x16x32_bf16 v[52:55], v[180:183], v[196:199], v[52:55]
	v_mfma_f32_16x16x32_bf16 v[48:51], v[188:191], v[196:199], v[48:51]
	v_mfma_f32_16x16x32_bf16 v[36:39], v[180:183], v[204:207], v[36:39]
	v_mfma_f32_16x16x32_bf16 v[32:35], v[188:191], v[204:207], v[32:35]
	v_mfma_f32_16x16x32_bf16 v[20:23], v[180:183], v[222:225], v[20:23]
	v_mfma_f32_16x16x32_bf16 v[16:19], v[188:191], v[222:225], v[16:19]
	v_mfma_f32_16x16x32_bf16 v[4:7], v[180:183], v[230:233], v[4:7]
	v_mfma_f32_16x16x32_bf16 v[0:3], v[188:191], v[230:233], v[0:3]
	s_setprio 0
	s_barrier
	s_add_i32 s76, 0, 0x18000
	v_add_u32_e32 v134, s76, v159
	s_add_i32 s77, 0, 0x1c000
	ds_read_b128 v[154:157], v134
	ds_read_b128 v[164:167], v134 offset:1024
	ds_read_b128 v[168:171], v134 offset:2048
	ds_read_b128 v[172:175], v134 offset:3072
	v_add_u32_e32 v134, s77, v159
	ds_read_b128 v[176:179], v134
	ds_read_b128 v[180:183], v134 offset:1024
	ds_read_b128 v[184:187], v134 offset:2048
	ds_read_b128 v[188:191], v134 offset:3072
	s_add_u32 s42, s42, 0x80000
	s_addc_u32 s43, s43, 0
	s_mov_b32 m0, s58
	v_lshl_add_u64 v[238:239], s[42:43], 0, v[146:147]
	ds_read_b128 v[192:195], v163 offset:32768
	ds_read_b128 v[196:199], v163 offset:33792
	ds_read_b128 v[200:203], v163 offset:34816
	ds_read_b128 v[204:207], v163 offset:35840
	ds_read_b128 v[218:221], v163 offset:36864
	ds_read_b128 v[222:225], v163 offset:37888
	ds_read_b128 v[226:229], v163 offset:38912
	ds_read_b128 v[230:233], v163 offset:39936
	global_load_lds_dwordx4 v[238:239], off
	v_lshl_add_u64 v[238:239], s[42:43], 0, v[144:145]
	s_mov_b32 m0, s59
	s_nop 0
	global_load_lds_dwordx4 v[238:239], off
	s_waitcnt vmcnt(8)
	s_waitcnt lgkmcnt(0)
	s_barrier
	s_setprio 1
	s_waitcnt lgkmcnt(0)
	v_mfma_f32_16x16x32_bf16 v[124:127], v[154:157], v[192:195], v[124:127]
	v_mfma_f32_16x16x32_bf16 v[120:123], v[168:171], v[192:195], v[120:123]
	v_mfma_f32_16x16x32_bf16 v[108:111], v[154:157], v[200:203], v[108:111]
	v_mfma_f32_16x16x32_bf16 v[104:107], v[168:171], v[200:203], v[104:107]
	v_mfma_f32_16x16x32_bf16 v[92:95], v[154:157], v[218:221], v[92:95]
	v_mfma_f32_16x16x32_bf16 v[88:91], v[168:171], v[218:221], v[88:91]
	v_mfma_f32_16x16x32_bf16 v[76:79], v[154:157], v[226:229], v[76:79]
	v_mfma_f32_16x16x32_bf16 v[72:75], v[168:171], v[226:229], v[72:75]
	v_mfma_f32_16x16x32_bf16 v[124:127], v[164:167], v[196:199], v[124:127]
	v_mfma_f32_16x16x32_bf16 v[120:123], v[172:175], v[196:199], v[120:123]
	v_mfma_f32_16x16x32_bf16 v[108:111], v[164:167], v[204:207], v[108:111]
	v_mfma_f32_16x16x32_bf16 v[104:107], v[172:175], v[204:207], v[104:107]
	v_mfma_f32_16x16x32_bf16 v[92:95], v[164:167], v[222:225], v[92:95]
	v_mfma_f32_16x16x32_bf16 v[88:91], v[172:175], v[222:225], v[88:91]
	v_mfma_f32_16x16x32_bf16 v[76:79], v[164:167], v[230:233], v[76:79]
	v_mfma_f32_16x16x32_bf16 v[72:75], v[172:175], v[230:233], v[72:75]
	s_setprio 0
	s_setprio 1
	v_mfma_f32_16x16x32_bf16 v[116:119], v[176:179], v[192:195], v[116:119]
	v_mfma_f32_16x16x32_bf16 v[112:115], v[184:187], v[192:195], v[112:115]
	v_mfma_f32_16x16x32_bf16 v[100:103], v[176:179], v[200:203], v[100:103]
	v_mfma_f32_16x16x32_bf16 v[96:99], v[184:187], v[200:203], v[96:99]
	v_mfma_f32_16x16x32_bf16 v[84:87], v[176:179], v[218:221], v[84:87]
	v_mfma_f32_16x16x32_bf16 v[80:83], v[184:187], v[218:221], v[80:83]
	v_mfma_f32_16x16x32_bf16 v[68:71], v[176:179], v[226:229], v[68:71]
	v_mfma_f32_16x16x32_bf16 v[64:67], v[184:187], v[226:229], v[64:67]
	v_mfma_f32_16x16x32_bf16 v[116:119], v[180:183], v[196:199], v[116:119]
	v_mfma_f32_16x16x32_bf16 v[112:115], v[188:191], v[196:199], v[112:115]
	v_mfma_f32_16x16x32_bf16 v[100:103], v[180:183], v[204:207], v[100:103]
	v_mfma_f32_16x16x32_bf16 v[96:99], v[188:191], v[204:207], v[96:99]
	v_mfma_f32_16x16x32_bf16 v[84:87], v[180:183], v[222:225], v[84:87]
	v_mfma_f32_16x16x32_bf16 v[80:83], v[188:191], v[222:225], v[80:83]
	v_mfma_f32_16x16x32_bf16 v[68:71], v[180:183], v[230:233], v[68:71]
	v_mfma_f32_16x16x32_bf16 v[64:67], v[188:191], v[230:233], v[64:67]
	s_setprio 0
	s_barrier
; #define PG8_STAGE(bufoff, gbase, voff) do { _Pragma("unroll") for (int _i = 0; _i < 2; ++_i) \
;         __builtin_amdgcn_global_load_lds((const unsigned*)((const char*)(gbase) + (voff)[_i]), (PG8_LAS unsigned*)(lds + (bufoff) + ldsw + _i * 8192), 16, 0, 0); } while (0)
; #define PG8_LDA(dst, b, h) do { _Pragma("unroll") for (int m = 0; m < 4; ++m) _Pragma("unroll") for (int k = 0; k < 2; ++k) dst[m][k] = *(const PG8_LAS bf16x8*)(lds + PG8_SA(b, h) + aoff + m * 2048 + k * 1024); } while (0)
; #define PG8_MMA(ai, bj, At, Bt) do { __builtin_amdgcn_s_setprio(1); _Pragma("unroll") for (int m = 0; m < 4; ++m) _Pragma("unroll") for (int n = 0; n < 2; ++n) _Pragma("unroll") for (int k = 0; k < 2; ++k) \
;         acc[ai][bj][m][n] = __builtin_amdgcn_mfma_f32_16x16x32_bf16(Bt[n][k], At[m][k], acc[ai][bj][m][n], 0, 0, 0); __builtin_amdgcn_s_setprio(0); } while (0)
; #define PG8_WAIT_V(n) asm volatile("s_waitcnt vmcnt(" #n ")" ::: "memory")
; #define PG8_WAIT_L(n) asm volatile("s_waitcnt lgkmcnt(" #n ")" ::: "memory")
; #define PG8_BAR __builtin_amdgcn_s_barrier()
; #define PG8_SCHED __builtin_amdgcn_sched_barrier(0)
; template <class Epi, class Sched, bool ALIGN_EPI = false, bool SP2 = false>
; __device__ __forceinline__ void gemm_phase(PG8_LAS unsigned char* lds, const Gemm g, const Sched& S, const Epi& E) {
;     ...
;         for (int t = 0; t < nt; t += 2) {
;     ...
;             PG8_LDA(At, 1, 1); PG8_STAGE(PG8_SB(1, 0), b3, voffB); PG8_STAGE(PG8_SB(1, 1), b3 + hstep, voffB); PG8_STAGE(PG8_SA(1, 0), a3, voffA);
;             PG8_WAIT_V(8); PG8_WAIT_L(0); PG8_BAR; PG8_MMA(1, 0, At, B0); PG8_MMA(1, 1, At, B1); PG8_BAR; PG8_SCHED;
	s_add_i32 s42, s76, s74
	v_lshl_add_u64 v[130:131], v[130:131], 0, s[78:79]
	s_mov_b32 m0, s42
	ds_read_b128 v[192:195], v163 offset:49152
	ds_read_b128 v[196:199], v163 offset:50176
	ds_read_b128 v[200:203], v163 offset:51200
	ds_read_b128 v[204:207], v163 offset:52224
	ds_read_b128 v[218:221], v163 offset:53248
	ds_read_b128 v[222:225], v163 offset:54272
	ds_read_b128 v[226:229], v163 offset:55296
	ds_read_b128 v[230:233], v163 offset:56320
	global_load_lds_dwordx4 v[130:131], off
	s_add_i32 m0, s42, 0x2000
	s_add_u32 s34, s34, 0x80080
	v_lshl_add_u64 v[130:131], v[132:133], 0, s[78:79]
	s_addc_u32 s35, s35, 0
	s_add_i32 s42, s77, s74
	global_load_lds_dwordx4 v[130:131], off
	v_lshl_add_u64 v[130:131], s[34:35], 0, v[128:129]
	s_mov_b32 m0, s42
	s_nop 0
	global_load_lds_dwordx4 v[130:131], off
	v_lshl_add_u64 v[130:131], s[34:35], 0, v[142:143]
	s_add_i32 m0, s42, 0x2000
	s_nop 0
	global_load_lds_dwordx4 v[130:131], off
	v_lshl_add_u64 v[130:131], v[234:235], 0, s[78:79]
	s_mov_b32 m0, s48
	s_nop 0
	global_load_lds_dwordx4 v[130:131], off
	v_lshl_add_u64 v[130:131], v[236:237], 0, s[78:79]
	s_mov_b32 m0, s36
	s_nop 0
	global_load_lds_dwordx4 v[130:131], off
	s_waitcnt vmcnt(8)
	s_waitcnt lgkmcnt(0)
	s_barrier
	s_setprio 1
	s_waitcnt lgkmcnt(0)
	v_mfma_f32_16x16x32_bf16 v[60:63], v[154:157], v[192:195], v[60:63]
	v_mfma_f32_16x16x32_bf16 v[56:59], v[168:171], v[192:195], v[56:59]
	v_mfma_f32_16x16x32_bf16 v[44:47], v[154:157], v[200:203], v[44:47]
	v_mfma_f32_16x16x32_bf16 v[40:43], v[168:171], v[200:203], v[40:43]
	v_mfma_f32_16x16x32_bf16 v[28:31], v[154:157], v[218:221], v[28:31]
	v_mfma_f32_16x16x32_bf16 v[24:27], v[168:171], v[218:221], v[24:27]
	v_mfma_f32_16x16x32_bf16 v[12:15], v[154:157], v[226:229], v[12:15]
	v_mfma_f32_16x16x32_bf16 v[8:11], v[168:171], v[226:229], v[8:11]
	v_mfma_f32_16x16x32_bf16 v[60:63], v[164:167], v[196:199], v[60:63]
	v_mfma_f32_16x16x32_bf16 v[56:59], v[172:175], v[196:199], v[56:59]
	v_mfma_f32_16x16x32_bf16 v[44:47], v[164:167], v[204:207], v[44:47]
	v_mfma_f32_16x16x32_bf16 v[40:43], v[172:175], v[204:207], v[40:43]
	v_mfma_f32_16x16x32_bf16 v[28:31], v[164:167], v[222:225], v[28:31]
	v_mfma_f32_16x16x32_bf16 v[24:27], v[172:175], v[222:225], v[24:27]
	v_mfma_f32_16x16x32_bf16 v[12:15], v[164:167], v[230:233], v[12:15]
	v_mfma_f32_16x16x32_bf16 v[8:11], v[172:175], v[230:233], v[8:11]
	s_setprio 0
	s_setprio 1
	v_mfma_f32_16x16x32_bf16 v[52:55], v[176:179], v[192:195], v[52:55]
	v_mfma_f32_16x16x32_bf16 v[48:51], v[184:187], v[192:195], v[48:51]
	v_mfma_f32_16x16x32_bf16 v[36:39], v[176:179], v[200:203], v[36:39]
	v_mfma_f32_16x16x32_bf16 v[32:35], v[184:187], v[200:203], v[32:35]
	v_mfma_f32_16x16x32_bf16 v[20:23], v[176:179], v[218:221], v[20:23]
	v_mfma_f32_16x16x32_bf16 v[16:19], v[184:187], v[218:221], v[16:19]
	v_mfma_f32_16x16x32_bf16 v[4:7], v[176:179], v[226:229], v[4:7]
	v_mfma_f32_16x16x32_bf16 v[0:3], v[184:187], v[226:229], v[0:3]
	v_mfma_f32_16x16x32_bf16 v[52:55], v[180:183], v[196:199], v[52:55]
	v_mfma_f32_16x16x32_bf16 v[48:51], v[188:191], v[196:199], v[48:51]
	v_mfma_f32_16x16x32_bf16 v[36:39], v[180:183], v[204:207], v[36:39]
	v_mfma_f32_16x16x32_bf16 v[32:35], v[188:191], v[204:207], v[32:35]
	v_mfma_f32_16x16x32_bf16 v[20:23], v[180:183], v[222:225], v[20:23]
	v_mfma_f32_16x16x32_bf16 v[16:19], v[188:191], v[222:225], v[16:19]
	v_mfma_f32_16x16x32_bf16 v[4:7], v[180:183], v[230:233], v[4:7]
	v_mfma_f32_16x16x32_bf16 v[0:3], v[188:191], v[230:233], v[0:3]
	s_setprio 0
	s_barrier
	s_add_i32 s69, s69, 2
	s_add_u32 s30, s30, 0x100
	s_addc_u32 s31, s31, 0
	s_add_u32 s62, s62, 0x100
	s_addc_u32 s68, s68, 0
	s_cmp_gt_u32 s69, 29

; template <class Epi, class Sched, bool ALIGN_EPI = false, bool SP2 = false>
; __device__ __forceinline__ void gemm_phase(PG8_LAS unsigned char* lds, const Gemm g, const Sched& S, const Epi& E) {
;     ...
;         const bool has_next = S.next(ui + 1, nxt);
;         const char* nA = has_next ? (const char*)g.A + (size_t)nxt.pm * tstep : cA; const char* nB = has_next ? (const char*)g.Bt + (size_t)nxt.pn * tstep : cB;
;         for (int t = 0; t < nt; t += 2) {
;             const bool last = (t == nt - 2);
;             const char* a1 = cA + (size_t)(t + 1) * kstep;
;             const char* a2 = last ? nA : cA + (size_t)(t + 2) * kstep; const char* b2 = last ? nB : cB + (size_t)(t + 2) * kstep;
;             const char* a3 = a2 + kstep; const char* b3 = b2 + kstep;
;     ...
; #pragma unroll
;         for (int a = 0; a < 2; ++a)
; #pragma unroll
;             for (int b = 0; b < 2; ++b)
; #pragma unroll
;                 for (int m = 0; m < 4; ++m)
; #pragma unroll
;                     for (int n = 0; n < 2; ++n) acc[a][b][m][n] = (f32x4){0.f, 0.f, 0.f, 0.f};
;         cur = nxt; cA = nA; cB = nB; ++ui;
.LBB0_1026:
	s_add_u32 s44, s26, 0x100

; template <class Epi, class Sched, bool ALIGN_EPI = false, bool SP2 = false>
; __device__ __forceinline__ void gemm_phase(PG8_LAS unsigned char* lds, const Gemm g, const Sched& S, const Epi& E) {
;     ...
; #pragma unroll
;         for (int a = 0; a < 2; ++a)
; #pragma unroll
;             for (int b = 0; b < 2; ++b)
; #pragma unroll
;                 for (int m = 0; m < 4; ++m)
; #pragma unroll
;                     for (int n = 0; n < 2; ++n) acc[a][b][m][n] = (f32x4){0.f, 0.f, 0.f, 0.f};
;         cur = nxt; cA = nA; cB = nB; ++ui;
	s_addc_u32 s45, s27, 0
	s_mov_b32 s74, -2
	s_waitcnt lgkmcnt(0)


; #define PG8_STAGE(bufoff, gbase, voff) do { _Pragma("unroll") for (int _i = 0; _i < 2; ++_i) \
;         __builtin_amdgcn_global_load_lds((const unsigned*)((const char*)(gbase) + (voff)[_i]), (PG8_LAS unsigned*)(lds + (bufoff) + ldsw + _i * 8192), 16, 0, 0); } while (0)
; #define PG8_LDA(dst, b, h) do { _Pragma("unroll") for (int m = 0; m < 4; ++m) _Pragma("unroll") for (int k = 0; k < 2; ++k) dst[m][k] = *(const PG8_LAS bf16x8*)(lds + PG8_SA(b, h) + aoff + m * 2048 + k * 1024); } while (0)
; #define PG8_LDB(dst, b, h) do { _Pragma("unroll") for (int n = 0; n < 2; ++n) _Pragma("unroll") for (int k = 0; k < 2; ++k) dst[n][k] = *(const PG8_LAS bf16x8*)(lds + PG8_SB(b, h) + boff + n * 2048 + k * 1024); } while (0)
; #define PG8_MMA(ai, bj, At, Bt) do { __builtin_amdgcn_s_setprio(1); _Pragma("unroll") for (int m = 0; m < 4; ++m) _Pragma("unroll") for (int n = 0; n < 2; ++n) _Pragma("unroll") for (int k = 0; k < 2; ++k) \
;         acc[ai][bj][m][n] = __builtin_amdgcn_mfma_f32_16x16x32_bf16(Bt[n][k], At[m][k], acc[ai][bj][m][n], 0, 0, 0); __builtin_amdgcn_s_setprio(0); } while (0)
; #define PG8_WAIT_V(n) asm volatile("s_waitcnt vmcnt(" #n ")" ::: "memory")
; #define PG8_BAR __builtin_amdgcn_s_barrier()
; template <class Epi, class Sched, bool ALIGN_EPI = false, bool SP2 = false>
; __device__ __forceinline__ void gemm_phase(PG8_LAS unsigned char* lds, const Gemm g, const Sched& S, const Epi& E) {
;     ...
;         for (int t = 0; t < nt; t += 2) {
;             const bool last = (t == nt - 2);
;             const char* a1 = cA + (size_t)(t + 1) * kstep;
;             const char* a2 = last ? nA : cA + (size_t)(t + 2) * kstep; const char* b2 = last ? nB : cB + (size_t)(t + 2) * kstep;
;             const char* a3 = a2 + kstep; const char* b3 = b2 + kstep;
;             if (last && has_next) S.a_ready(nxt);
;             if constexpr (SP2) {
;             PG8_LDB(B0, 0, 0); PG8_LDB(B1, 0, 1); PG8_SCHED; PG8_LDA(At, 0, 0); PG8_STAGE(PG8_SA(1, 1), a1 + hstep, voffA);
;             PG8_WAIT_V(8); PG8_WAIT_L(0); PG8_BAR; PG8_MMA(0, 0, At, B0); PG8_MMA(0, 1, At, B1); PG8_BAR; PG8_SCHED;
;             PG8_LDA(At, 0, 1); PG8_STAGE(PG8_SB(0, 0), b2, voffB); PG8_STAGE(PG8_SB(0, 1), b2 + hstep, voffB); PG8_STAGE(PG8_SA(0, 0), a2, voffA);
;             PG8_WAIT_V(8); PG8_WAIT_L(0); PG8_BAR; PG8_MMA(1, 0, At, B0); PG8_MMA(1, 1, At, B1); PG8_BAR; PG8_SCHED;
	s_add_u32 s26, s24, 0x100
	s_addc_u32 s27, s25, 0
	s_add_i32 s77, 0, 0x10000
	s_cmpk_eq_i32 s74, 0x54
	s_cselect_b32 s31, s21, s27
	s_cselect_b32 s30, s20, s26
	v_add_u32_e32 v130, s77, v191
	s_cselect_b32 s29, s23, s45
	s_cselect_b32 s28, s22, s44
	s_add_i32 vcc_lo, 0, 0x14000
	ds_read_b128 v[148:151], v130
	ds_read_b128 v[152:155], v130 offset:1024
	ds_read_b128 v[156:159], v130 offset:2048
	ds_read_b128 v[160:163], v130 offset:3072
	v_add_u32_e32 v130, vcc_lo, v191
	ds_read_b128 v[164:167], v130
	ds_read_b128 v[168:171], v130 offset:1024
	ds_read_b128 v[172:175], v130 offset:2048
	ds_read_b128 v[176:179], v130 offset:3072
	v_lshl_add_u64 v[130:131], s[24:25], 0, v[144:145]
	s_add_i32 m0, s55, 0xc000
	ds_read_b128 v[180:183], v193
	ds_read_b128 v[184:187], v193 offset:1024
	ds_read_b128 v[194:197], v193 offset:2048
	ds_read_b128 v[198:201], v193 offset:3072
	ds_read_b128 v[202:205], v193 offset:4096
	ds_read_b128 v[218:221], v193 offset:5120
	ds_read_b128 v[222:225], v193 offset:6144
	ds_read_b128 v[226:229], v193 offset:7168
	global_load_lds_dwordx4 v[130:131], off
	v_lshl_add_u64 v[130:131], s[24:25], 0, v[146:147]
	s_add_i32 m0, s55, 0xe000
	s_nop 0
	global_load_lds_dwordx4 v[130:131], off
	s_waitcnt vmcnt(8)
	s_waitcnt lgkmcnt(0)
	s_barrier
	s_setprio 1
	s_waitcnt lgkmcnt(0)
	v_mfma_f32_16x16x32_bf16 v[124:127], v[148:151], v[180:183], 0
	v_mfma_f32_16x16x32_bf16 v[120:123], v[156:159], v[180:183], 0
	v_mfma_f32_16x16x32_bf16 v[108:111], v[148:151], v[194:197], 0
	v_mfma_f32_16x16x32_bf16 v[104:107], v[156:159], v[194:197], 0
	v_mfma_f32_16x16x32_bf16 v[92:95], v[148:151], v[202:205], 0
	v_mfma_f32_16x16x32_bf16 v[88:91], v[156:159], v[202:205], 0
	v_mfma_f32_16x16x32_bf16 v[76:79], v[148:151], v[222:225], 0
	v_mfma_f32_16x16x32_bf16 v[72:75], v[156:159], v[222:225], 0
	v_mfma_f32_16x16x32_bf16 v[124:127], v[152:155], v[184:187], v[124:127]
	v_mfma_f32_16x16x32_bf16 v[120:123], v[160:163], v[184:187], v[120:123]
	v_mfma_f32_16x16x32_bf16 v[108:111], v[152:155], v[198:201], v[108:111]
	v_mfma_f32_16x16x32_bf16 v[104:107], v[160:163], v[198:201], v[104:107]
	v_mfma_f32_16x16x32_bf16 v[92:95], v[152:155], v[218:221], v[92:95]
	v_mfma_f32_16x16x32_bf16 v[88:91], v[160:163], v[218:221], v[88:91]
	v_mfma_f32_16x16x32_bf16 v[76:79], v[152:155], v[226:229], v[76:79]
	v_mfma_f32_16x16x32_bf16 v[72:75], v[160:163], v[226:229], v[72:75]
	s_setprio 0
	s_setprio 1
	v_mfma_f32_16x16x32_bf16 v[116:119], v[164:167], v[180:183], 0
	v_mfma_f32_16x16x32_bf16 v[112:115], v[172:175], v[180:183], 0
	v_mfma_f32_16x16x32_bf16 v[100:103], v[164:167], v[194:197], 0
	v_mfma_f32_16x16x32_bf16 v[96:99], v[172:175], v[194:197], 0
	v_mfma_f32_16x16x32_bf16 v[84:87], v[164:167], v[202:205], 0
	v_mfma_f32_16x16x32_bf16 v[80:83], v[172:175], v[202:205], 0
	v_mfma_f32_16x16x32_bf16 v[68:71], v[164:167], v[222:225], 0
	v_mfma_f32_16x16x32_bf16 v[64:67], v[172:175], v[222:225], 0
	v_mfma_f32_16x16x32_bf16 v[116:119], v[168:171], v[184:187], v[116:119]
	v_mfma_f32_16x16x32_bf16 v[112:115], v[176:179], v[184:187], v[112:115]
	v_mfma_f32_16x16x32_bf16 v[100:103], v[168:171], v[198:201], v[100:103]
	v_mfma_f32_16x16x32_bf16 v[96:99], v[176:179], v[198:201], v[96:99]
	v_mfma_f32_16x16x32_bf16 v[84:87], v[168:171], v[218:221], v[84:87]
	v_mfma_f32_16x16x32_bf16 v[80:83], v[176:179], v[218:221], v[80:83]
	v_mfma_f32_16x16x32_bf16 v[68:71], v[168:171], v[226:229], v[68:71]
	v_mfma_f32_16x16x32_bf16 v[64:67], v[176:179], v[226:229], v[64:67]
	s_setprio 0
	s_barrier
	s_add_i32 s24, s77, s54
	v_lshl_add_u64 v[130:131], s[28:29], 0, v[128:129]
	s_mov_b32 m0, s24
	ds_read_b128 v[180:183], v193 offset:16384
	ds_read_b128 v[184:187], v193 offset:17408
	ds_read_b128 v[194:197], v193 offset:18432
	ds_read_b128 v[198:201], v193 offset:19456
	ds_read_b128 v[202:205], v193 offset:20480
	ds_read_b128 v[218:221], v193 offset:21504
	ds_read_b128 v[222:225], v193 offset:22528
	ds_read_b128 v[226:229], v193 offset:23552
	global_load_lds_dwordx4 v[130:131], off
	s_add_i32 m0, s24, 0x2000
	s_add_u32 s24, s28, 0x160000
	v_lshl_add_u64 v[132:133], s[28:29], 0, v[142:143]
	s_addc_u32 s25, s29, 0
	s_add_i32 s77, vcc_lo, s54
	global_load_lds_dwordx4 v[132:133], off
	v_lshl_add_u64 v[188:189], s[24:25], 0, v[128:129]
	s_mov_b32 m0, s77
	v_lshl_add_u64 v[206:207], s[30:31], 0, v[142:143]
	global_load_lds_dwordx4 v[188:189], off
	v_lshl_add_u64 v[188:189], s[24:25], 0, v[142:143]
	s_add_i32 m0, s77, 0x2000
	s_nop 0
	global_load_lds_dwordx4 v[188:189], off
	v_lshl_add_u64 v[188:189], s[30:31], 0, v[128:129]
	s_mov_b32 m0, s55
	s_nop 0
	global_load_lds_dwordx4 v[188:189], off
	s_mov_b32 m0, s56
	s_nop 0
	global_load_lds_dwordx4 v[206:207], off
	s_waitcnt vmcnt(8)
	s_waitcnt lgkmcnt(0)
	s_barrier
; #define PG8_STAGE(bufoff, gbase, voff) do { _Pragma("unroll") for (int _i = 0; _i < 2; ++_i) \
;         __builtin_amdgcn_global_load_lds((const unsigned*)((const char*)(gbase) + (voff)[_i]), (PG8_LAS unsigned*)(lds + (bufoff) + ldsw + _i * 8192), 16, 0, 0); } while (0)
; #define PG8_LDA(dst, b, h) do { _Pragma("unroll") for (int m = 0; m < 4; ++m) _Pragma("unroll") for (int k = 0; k < 2; ++k) dst[m][k] = *(const PG8_LAS bf16x8*)(lds + PG8_SA(b, h) + aoff + m * 2048 + k * 1024); } while (0)
; #define PG8_LDB(dst, b, h) do { _Pragma("unroll") for (int n = 0; n < 2; ++n) _Pragma("unroll") for (int k = 0; k < 2; ++k) dst[n][k] = *(const PG8_LAS bf16x8*)(lds + PG8_SB(b, h) + boff + n * 2048 + k * 1024); } while (0)
; #define PG8_MMA(ai, bj, At, Bt) do { __builtin_amdgcn_s_setprio(1); _Pragma("unroll") for (int m = 0; m < 4; ++m) _Pragma("unroll") for (int n = 0; n < 2; ++n) _Pragma("unroll") for (int k = 0; k < 2; ++k) \
;         acc[ai][bj][m][n] = __builtin_amdgcn_mfma_f32_16x16x32_bf16(Bt[n][k], At[m][k], acc[ai][bj][m][n], 0, 0, 0); __builtin_amdgcn_s_setprio(0); } while (0)
; #define PG8_WAIT_V(n) asm volatile("s_waitcnt vmcnt(" #n ")" ::: "memory")
; #define PG8_WAIT_L(n) asm volatile("s_waitcnt lgkmcnt(" #n ")" ::: "memory")
; #define PG8_BAR __builtin_amdgcn_s_barrier()
; #define PG8_SCHED __builtin_amdgcn_sched_barrier(0)
; template <class Epi, class Sched, bool ALIGN_EPI = false, bool SP2 = false>
; __device__ __forceinline__ void gemm_phase(PG8_LAS unsigned char* lds, const Gemm g, const Sched& S, const Epi& E) {
;     ...
;             PG8_WAIT_V(8); PG8_WAIT_L(0); PG8_BAR; PG8_MMA(1, 0, At, B0); PG8_MMA(1, 1, At, B1); PG8_BAR; PG8_SCHED;
;             PG8_LDB(B0, 1, 0); PG8_LDB(B1, 1, 1); PG8_SCHED; PG8_LDA(At, 1, 0); PG8_STAGE(PG8_SA(0, 1), a2 + hstep, voffA);
;             PG8_WAIT_V(8); PG8_WAIT_L(0); PG8_BAR; PG8_MMA(0, 0, At, B0); PG8_MMA(0, 1, At, B1); PG8_BAR; PG8_SCHED;
	s_setprio 1
	s_waitcnt lgkmcnt(0)
	v_mfma_f32_16x16x32_bf16 v[60:63], v[148:151], v[180:183], 0
	v_mfma_f32_16x16x32_bf16 v[56:59], v[156:159], v[180:183], 0
	v_mfma_f32_16x16x32_bf16 v[44:47], v[148:151], v[194:197], 0
	v_mfma_f32_16x16x32_bf16 v[40:43], v[156:159], v[194:197], 0
	v_mfma_f32_16x16x32_bf16 v[28:31], v[148:151], v[202:205], 0
	v_mfma_f32_16x16x32_bf16 v[24:27], v[156:159], v[202:205], 0
	v_mfma_f32_16x16x32_bf16 v[12:15], v[148:151], v[222:225], 0
	v_mfma_f32_16x16x32_bf16 v[8:11], v[156:159], v[222:225], 0
	v_mfma_f32_16x16x32_bf16 v[60:63], v[152:155], v[184:187], v[60:63]
	v_mfma_f32_16x16x32_bf16 v[56:59], v[160:163], v[184:187], v[56:59]
	v_mfma_f32_16x16x32_bf16 v[44:47], v[152:155], v[198:201], v[44:47]
	v_mfma_f32_16x16x32_bf16 v[40:43], v[160:163], v[198:201], v[40:43]
	v_mfma_f32_16x16x32_bf16 v[28:31], v[152:155], v[218:221], v[28:31]
	v_mfma_f32_16x16x32_bf16 v[24:27], v[160:163], v[218:221], v[24:27]
	v_mfma_f32_16x16x32_bf16 v[12:15], v[152:155], v[226:229], v[12:15]
	v_mfma_f32_16x16x32_bf16 v[8:11], v[160:163], v[226:229], v[8:11]
	s_setprio 0
	s_setprio 1
	v_mfma_f32_16x16x32_bf16 v[52:55], v[164:167], v[180:183], 0
	v_mfma_f32_16x16x32_bf16 v[48:51], v[172:175], v[180:183], 0
	v_mfma_f32_16x16x32_bf16 v[36:39], v[164:167], v[194:197], 0
	v_mfma_f32_16x16x32_bf16 v[32:35], v[172:175], v[194:197], 0
	v_mfma_f32_16x16x32_bf16 v[20:23], v[164:167], v[202:205], 0
	v_mfma_f32_16x16x32_bf16 v[16:19], v[172:175], v[202:205], 0
	v_mfma_f32_16x16x32_bf16 v[4:7], v[164:167], v[222:225], 0
	v_mfma_f32_16x16x32_bf16 v[0:3], v[172:175], v[222:225], 0
	v_mfma_f32_16x16x32_bf16 v[52:55], v[168:171], v[184:187], v[52:55]
	v_mfma_f32_16x16x32_bf16 v[48:51], v[176:179], v[184:187], v[48:51]
	v_mfma_f32_16x16x32_bf16 v[36:39], v[168:171], v[198:201], v[36:39]
	v_mfma_f32_16x16x32_bf16 v[32:35], v[176:179], v[198:201], v[32:35]
	v_mfma_f32_16x16x32_bf16 v[20:23], v[168:171], v[218:221], v[20:23]
	v_mfma_f32_16x16x32_bf16 v[16:19], v[176:179], v[218:221], v[16:19]
	v_mfma_f32_16x16x32_bf16 v[4:7], v[168:171], v[226:229], v[4:7]
	v_mfma_f32_16x16x32_bf16 v[0:3], v[176:179], v[226:229], v[0:3]
	s_setprio 0
	s_barrier
	s_add_i32 s77, 0, 0x18000
	v_add_u32_e32 v134, s77, v191
	s_add_i32 vcc_lo, 0, 0x1c000
	ds_read_b128 v[148:151], v134
	ds_read_b128 v[152:155], v134 offset:1024
	ds_read_b128 v[156:159], v134 offset:2048
	ds_read_b128 v[160:163], v134 offset:3072
	v_add_u32_e32 v134, vcc_lo, v191
	ds_read_b128 v[164:167], v134
	ds_read_b128 v[168:171], v134 offset:1024
	ds_read_b128 v[172:175], v134 offset:2048
	ds_read_b128 v[176:179], v134 offset:3072
	s_add_u32 s24, s30, 0x160000
	s_addc_u32 s25, s31, 0
	s_mov_b32 m0, s57
	v_lshl_add_u64 v[230:231], s[24:25], 0, v[128:129]
	ds_read_b128 v[180:183], v193 offset:32768
	ds_read_b128 v[184:187], v193 offset:33792
	ds_read_b128 v[194:197], v193 offset:34816
	ds_read_b128 v[198:201], v193 offset:35840
	ds_read_b128 v[202:205], v193 offset:36864
	ds_read_b128 v[218:221], v193 offset:37888
	ds_read_b128 v[222:225], v193 offset:38912
	ds_read_b128 v[226:229], v193 offset:39936
	global_load_lds_dwordx4 v[230:231], off
	v_lshl_add_u64 v[230:231], s[24:25], 0, v[142:143]
	s_mov_b32 m0, s58
	s_nop 0
	global_load_lds_dwordx4 v[230:231], off
	s_waitcnt vmcnt(8)
	s_waitcnt lgkmcnt(0)
	s_barrier
	s_setprio 1
	s_waitcnt lgkmcnt(0)
	v_mfma_f32_16x16x32_bf16 v[124:127], v[148:151], v[180:183], v[124:127]
	v_mfma_f32_16x16x32_bf16 v[120:123], v[156:159], v[180:183], v[120:123]
	v_mfma_f32_16x16x32_bf16 v[108:111], v[148:151], v[194:197], v[108:111]
	v_mfma_f32_16x16x32_bf16 v[104:107], v[156:159], v[194:197], v[104:107]
	v_mfma_f32_16x16x32_bf16 v[92:95], v[148:151], v[202:205], v[92:95]
	v_mfma_f32_16x16x32_bf16 v[88:91], v[156:159], v[202:205], v[88:91]
	v_mfma_f32_16x16x32_bf16 v[76:79], v[148:151], v[222:225], v[76:79]
	v_mfma_f32_16x16x32_bf16 v[72:75], v[156:159], v[222:225], v[72:75]
	v_mfma_f32_16x16x32_bf16 v[124:127], v[152:155], v[184:187], v[124:127]
	v_mfma_f32_16x16x32_bf16 v[120:123], v[160:163], v[184:187], v[120:123]
	v_mfma_f32_16x16x32_bf16 v[108:111], v[152:155], v[198:201], v[108:111]
	v_mfma_f32_16x16x32_bf16 v[104:107], v[160:163], v[198:201], v[104:107]
	v_mfma_f32_16x16x32_bf16 v[92:95], v[152:155], v[218:221], v[92:95]
	v_mfma_f32_16x16x32_bf16 v[88:91], v[160:163], v[218:221], v[88:91]
	v_mfma_f32_16x16x32_bf16 v[76:79], v[152:155], v[226:229], v[76:79]
	v_mfma_f32_16x16x32_bf16 v[72:75], v[160:163], v[226:229], v[72:75]
	s_setprio 0
	s_setprio 1
	v_mfma_f32_16x16x32_bf16 v[116:119], v[164:167], v[180:183], v[116:119]
	v_mfma_f32_16x16x32_bf16 v[112:115], v[172:175], v[180:183], v[112:115]
	v_mfma_f32_16x16x32_bf16 v[100:103], v[164:167], v[194:197], v[100:103]
	v_mfma_f32_16x16x32_bf16 v[96:99], v[172:175], v[194:197], v[96:99]
	v_mfma_f32_16x16x32_bf16 v[84:87], v[164:167], v[202:205], v[84:87]
	v_mfma_f32_16x16x32_bf16 v[80:83], v[172:175], v[202:205], v[80:83]
	v_mfma_f32_16x16x32_bf16 v[68:71], v[164:167], v[222:225], v[68:71]
	v_mfma_f32_16x16x32_bf16 v[64:67], v[172:175], v[222:225], v[64:67]
	v_mfma_f32_16x16x32_bf16 v[116:119], v[168:171], v[184:187], v[116:119]
	v_mfma_f32_16x16x32_bf16 v[112:115], v[176:179], v[184:187], v[112:115]
	v_mfma_f32_16x16x32_bf16 v[100:103], v[168:171], v[198:201], v[100:103]
	v_mfma_f32_16x16x32_bf16 v[96:99], v[176:179], v[198:201], v[96:99]
	v_mfma_f32_16x16x32_bf16 v[84:87], v[168:171], v[218:221], v[84:87]
	v_mfma_f32_16x16x32_bf16 v[80:83], v[176:179], v[218:221], v[80:83]
	v_mfma_f32_16x16x32_bf16 v[68:71], v[168:171], v[226:229], v[68:71]
	v_mfma_f32_16x16x32_bf16 v[64:67], v[176:179], v[226:229], v[64:67]
	s_setprio 0
	s_barrier
; #define PG8_STAGE(bufoff, gbase, voff) do { _Pragma("unroll") for (int _i = 0; _i < 2; ++_i) \
;         __builtin_amdgcn_global_load_lds((const unsigned*)((const char*)(gbase) + (voff)[_i]), (PG8_LAS unsigned*)(lds + (bufoff) + ldsw + _i * 8192), 16, 0, 0); } while (0)
; #define PG8_LDA(dst, b, h) do { _Pragma("unroll") for (int m = 0; m < 4; ++m) _Pragma("unroll") for (int k = 0; k < 2; ++k) dst[m][k] = *(const PG8_LAS bf16x8*)(lds + PG8_SA(b, h) + aoff + m * 2048 + k * 1024); } while (0)
; #define PG8_MMA(ai, bj, At, Bt) do { __builtin_amdgcn_s_setprio(1); _Pragma("unroll") for (int m = 0; m < 4; ++m) _Pragma("unroll") for (int n = 0; n < 2; ++n) _Pragma("unroll") for (int k = 0; k < 2; ++k) \
;         acc[ai][bj][m][n] = __builtin_amdgcn_mfma_f32_16x16x32_bf16(Bt[n][k], At[m][k], acc[ai][bj][m][n], 0, 0, 0); __builtin_amdgcn_s_setprio(0); } while (0)
; #define PG8_WAIT_V(n) asm volatile("s_waitcnt vmcnt(" #n ")" ::: "memory")
; #define PG8_WAIT_L(n) asm volatile("s_waitcnt lgkmcnt(" #n ")" ::: "memory")
; #define PG8_BAR __builtin_amdgcn_s_barrier()
; #define PG8_SCHED __builtin_amdgcn_sched_barrier(0)
; template <class Epi, class Sched, bool ALIGN_EPI = false, bool SP2 = false>
; __device__ __forceinline__ void gemm_phase(PG8_LAS unsigned char* lds, const Gemm g, const Sched& S, const Epi& E) {
;     ...
;         for (int t = 0; t < nt; t += 2) {
;     ...
;             PG8_LDA(At, 1, 1); PG8_STAGE(PG8_SB(1, 0), b3, voffB); PG8_STAGE(PG8_SB(1, 1), b3 + hstep, voffB); PG8_STAGE(PG8_SA(1, 0), a3, voffA);
;             PG8_WAIT_V(8); PG8_WAIT_L(0); PG8_BAR; PG8_MMA(1, 0, At, B0); PG8_MMA(1, 1, At, B1); PG8_BAR; PG8_SCHED;
	s_add_i32 s24, s77, s54
	v_lshl_add_u64 v[130:131], v[130:131], 0, s[78:79]
	s_mov_b32 m0, s24
	ds_read_b128 v[180:183], v193 offset:49152
	ds_read_b128 v[184:187], v193 offset:50176
	ds_read_b128 v[194:197], v193 offset:51200
	ds_read_b128 v[198:201], v193 offset:52224
	ds_read_b128 v[202:205], v193 offset:53248
	ds_read_b128 v[218:221], v193 offset:54272
	ds_read_b128 v[222:225], v193 offset:55296
	ds_read_b128 v[226:229], v193 offset:56320
	global_load_lds_dwordx4 v[130:131], off
	s_add_i32 m0, s24, 0x2000
	s_add_u32 s24, s28, 0x160080
	v_lshl_add_u64 v[130:131], v[132:133], 0, s[78:79]
	s_addc_u32 s25, s29, 0
	s_add_i32 s28, vcc_lo, s54
	global_load_lds_dwordx4 v[130:131], off
	v_lshl_add_u64 v[130:131], s[24:25], 0, v[128:129]
	s_mov_b32 m0, s28
	s_nop 0
	global_load_lds_dwordx4 v[130:131], off
	v_lshl_add_u64 v[130:131], s[24:25], 0, v[142:143]
	s_add_i32 m0, s28, 0x2000
	s_nop 0
	global_load_lds_dwordx4 v[130:131], off
	v_lshl_add_u64 v[130:131], v[188:189], 0, s[78:79]
	s_mov_b32 m0, s60
	s_nop 0
	global_load_lds_dwordx4 v[130:131], off
	v_lshl_add_u64 v[130:131], v[206:207], 0, s[78:79]
	s_mov_b32 m0, s61
	s_nop 0
	global_load_lds_dwordx4 v[130:131], off
	s_waitcnt vmcnt(8)
	s_waitcnt lgkmcnt(0)
	s_barrier
	s_setprio 1
	s_waitcnt lgkmcnt(0)
	v_mfma_f32_16x16x32_bf16 v[60:63], v[148:151], v[180:183], v[60:63]
	v_mfma_f32_16x16x32_bf16 v[56:59], v[156:159], v[180:183], v[56:59]
	v_mfma_f32_16x16x32_bf16 v[44:47], v[148:151], v[194:197], v[44:47]
	v_mfma_f32_16x16x32_bf16 v[40:43], v[156:159], v[194:197], v[40:43]
	v_mfma_f32_16x16x32_bf16 v[28:31], v[148:151], v[202:205], v[28:31]
	v_mfma_f32_16x16x32_bf16 v[24:27], v[156:159], v[202:205], v[24:27]
	v_mfma_f32_16x16x32_bf16 v[12:15], v[148:151], v[222:225], v[12:15]
	v_mfma_f32_16x16x32_bf16 v[8:11], v[156:159], v[222:225], v[8:11]
	v_mfma_f32_16x16x32_bf16 v[60:63], v[152:155], v[184:187], v[60:63]
	v_mfma_f32_16x16x32_bf16 v[56:59], v[160:163], v[184:187], v[56:59]
	v_mfma_f32_16x16x32_bf16 v[44:47], v[152:155], v[198:201], v[44:47]
	v_mfma_f32_16x16x32_bf16 v[40:43], v[160:163], v[198:201], v[40:43]
	v_mfma_f32_16x16x32_bf16 v[28:31], v[152:155], v[218:221], v[28:31]
	v_mfma_f32_16x16x32_bf16 v[24:27], v[160:163], v[218:221], v[24:27]
	v_mfma_f32_16x16x32_bf16 v[12:15], v[152:155], v[226:229], v[12:15]
	v_mfma_f32_16x16x32_bf16 v[8:11], v[160:163], v[226:229], v[8:11]
	s_setprio 0
	s_setprio 1
	v_mfma_f32_16x16x32_bf16 v[52:55], v[164:167], v[180:183], v[52:55]
	v_mfma_f32_16x16x32_bf16 v[48:51], v[172:175], v[180:183], v[48:51]
	v_mfma_f32_16x16x32_bf16 v[36:39], v[164:167], v[194:197], v[36:39]
	v_mfma_f32_16x16x32_bf16 v[32:35], v[172:175], v[194:197], v[32:35]
	v_mfma_f32_16x16x32_bf16 v[20:23], v[164:167], v[202:205], v[20:23]
	v_mfma_f32_16x16x32_bf16 v[16:19], v[172:175], v[202:205], v[16:19]
	v_mfma_f32_16x16x32_bf16 v[4:7], v[164:167], v[222:225], v[4:7]
	v_mfma_f32_16x16x32_bf16 v[0:3], v[172:175], v[222:225], v[0:3]
	v_mfma_f32_16x16x32_bf16 v[52:55], v[168:171], v[184:187], v[52:55]
	v_mfma_f32_16x16x32_bf16 v[48:51], v[176:179], v[184:187], v[48:51]
	v_mfma_f32_16x16x32_bf16 v[36:39], v[168:171], v[198:201], v[36:39]
	v_mfma_f32_16x16x32_bf16 v[32:35], v[176:179], v[198:201], v[32:35]
	v_mfma_f32_16x16x32_bf16 v[20:23], v[168:171], v[218:221], v[20:23]
	v_mfma_f32_16x16x32_bf16 v[16:19], v[176:179], v[218:221], v[16:19]
	v_mfma_f32_16x16x32_bf16 v[4:7], v[168:171], v[226:229], v[4:7]
	v_mfma_f32_16x16x32_bf16 v[0:3], v[176:179], v[226:229], v[0:3]
	s_setprio 0
	s_barrier
	s_add_i32 s74, s74, 2
	s_add_u32 s44, s44, 0x100
	s_addc_u32 s45, s45, 0
	s_cmpk_gt_u32 s74, 0x55
	s_mov_b64 s[24:25], s[26:27]

; template <class Epi, class Sched, bool ALIGN_EPI = false, bool SP2 = false>
; __device__ __forceinline__ void gemm_phase(PG8_LAS unsigned char* lds, const Gemm g, const Sched& S, const Epi& E) {
;     ...
;         const bool has_next = S.next(ui + 1, nxt);
;         const char* nA = has_next ? (const char*)g.A + (size_t)nxt.pm * tstep : cA; const char* nB = has_next ? (const char*)g.Bt + (size_t)nxt.pn * tstep : cB;
;         for (int t = 0; t < nt; t += 2) {
;             const bool last = (t == nt - 2);
;             const char* a1 = cA + (size_t)(t + 1) * kstep;
;             const char* a2 = last ? nA : cA + (size_t)(t + 2) * kstep; const char* b2 = last ? nB : cB + (size_t)(t + 2) * kstep;
;             const char* a3 = a2 + kstep; const char* b3 = b2 + kstep;
;     ...
; #pragma unroll
;         for (int a = 0; a < 2; ++a)
; #pragma unroll
;             for (int b = 0; b < 2; ++b)
; #pragma unroll
;                 for (int m = 0; m < 4; ++m)
; #pragma unroll
;                     for (int n = 0; n < 2; ++n) acc[a][b][m][n] = (f32x4){0.f, 0.f, 0.f, 0.f};
;         cur = nxt; cA = nA; cB = nB; ++ui;
.LBB0_1121:
	s_ashr_i32 s23, s22, 31
	s_lshl_b64 s[24:25], s[22:23], 20
	s_add_u32 s24, s38, s24
	s_addc_u32 s25, s39, s25
	s_and_b64 s[26:27], s[40:41], exec
	s_cselect_b32 s23, s25, s31
	s_cselect_b32 s61, s24, s30
	s_ashr_i32 s21, s20, 31
	s_lshl_b64 s[26:27], s[20:21], 20
	s_add_u32 s26, s44, s26
	s_addc_u32 s27, s45, s27
	s_and_b64 s[42:43], s[40:41], exec
	s_cselect_b32 s21, s27, s35
	s_cselect_b32 s62, s26, s34
	s_add_u32 s30, s30, 0x80080
	s_addc_u32 s31, s31, 0
	s_add_u32 s68, s34, 0x100

; template <class Epi, class Sched, bool ALIGN_EPI = false, bool SP2 = false>
; __device__ __forceinline__ void gemm_phase(PG8_LAS unsigned char* lds, const Gemm g, const Sched& S, const Epi& E) {
;     ...
; #pragma unroll
;         for (int a = 0; a < 2; ++a)
; #pragma unroll
;             for (int b = 0; b < 2; ++b)
; #pragma unroll
;                 for (int m = 0; m < 4; ++m)
; #pragma unroll
;                     for (int n = 0; n < 2; ++n) acc[a][b][m][n] = (f32x4){0.f, 0.f, 0.f, 0.f};
;         cur = nxt; cA = nA; cB = nB; ++ui;
	s_addc_u32 s69, s35, 0
	s_mov_b32 s74, -2


; #define PG8_STAGE(bufoff, gbase, voff) do { _Pragma("unroll") for (int _i = 0; _i < 2; ++_i) \
;         __builtin_amdgcn_global_load_lds((const unsigned*)((const char*)(gbase) + (voff)[_i]), (PG8_LAS unsigned*)(lds + (bufoff) + ldsw + _i * 8192), 16, 0, 0); } while (0)
; #define PG8_LDA(dst, b, h) do { _Pragma("unroll") for (int m = 0; m < 4; ++m) _Pragma("unroll") for (int k = 0; k < 2; ++k) dst[m][k] = *(const PG8_LAS bf16x8*)(lds + PG8_SA(b, h) + aoff + m * 2048 + k * 1024); } while (0)
; #define PG8_LDB(dst, b, h) do { _Pragma("unroll") for (int n = 0; n < 2; ++n) _Pragma("unroll") for (int k = 0; k < 2; ++k) dst[n][k] = *(const PG8_LAS bf16x8*)(lds + PG8_SB(b, h) + boff + n * 2048 + k * 1024); } while (0)
; #define PG8_MMA(ai, bj, At, Bt) do { __builtin_amdgcn_s_setprio(1); _Pragma("unroll") for (int m = 0; m < 4; ++m) _Pragma("unroll") for (int n = 0; n < 2; ++n) _Pragma("unroll") for (int k = 0; k < 2; ++k) \
;         acc[ai][bj][m][n] = __builtin_amdgcn_mfma_f32_16x16x32_bf16(Bt[n][k], At[m][k], acc[ai][bj][m][n], 0, 0, 0); __builtin_amdgcn_s_setprio(0); } while (0)
; #define PG8_WAIT_V(n) asm volatile("s_waitcnt vmcnt(" #n ")" ::: "memory")
; #define PG8_BAR __builtin_amdgcn_s_barrier()
; template <class Epi, class Sched, bool ALIGN_EPI = false, bool SP2 = false>
; __device__ __forceinline__ void gemm_phase(PG8_LAS unsigned char* lds, const Gemm g, const Sched& S, const Epi& E) {
;     ...
;         for (int t = 0; t < nt; t += 2) {
;             const bool last = (t == nt - 2);
;             const char* a1 = cA + (size_t)(t + 1) * kstep;
;             const char* a2 = last ? nA : cA + (size_t)(t + 2) * kstep; const char* b2 = last ? nB : cB + (size_t)(t + 2) * kstep;
;             const char* a3 = a2 + kstep; const char* b3 = b2 + kstep;
;             if (last && has_next) S.a_ready(nxt);
;             if constexpr (SP2) {
;             PG8_LDB(B0, 0, 0); PG8_LDB(B1, 0, 1); PG8_SCHED; PG8_LDA(At, 0, 0); PG8_STAGE(PG8_SA(1, 1), a1 + hstep, voffA);
;             PG8_WAIT_V(8); PG8_WAIT_L(0); PG8_BAR; PG8_MMA(0, 0, At, B0); PG8_MMA(0, 1, At, B1); PG8_BAR; PG8_SCHED;
;             PG8_LDA(At, 0, 1); PG8_STAGE(PG8_SB(0, 0), b2, voffB); PG8_STAGE(PG8_SB(0, 1), b2 + hstep, voffB); PG8_STAGE(PG8_SA(0, 0), a2, voffA);
;             PG8_WAIT_V(8); PG8_WAIT_L(0); PG8_BAR; PG8_MMA(1, 0, At, B0); PG8_MMA(1, 1, At, B1); PG8_BAR; PG8_SCHED;
	s_add_u32 s34, s30, 0xfff80080
	s_addc_u32 s35, s31, -1
	s_add_i32 s76, 0, 0x10000
	s_cmp_eq_u32 s74, 28
	s_cselect_b32 s43, s23, s35
	s_cselect_b32 s42, s61, s34
	v_add_u32_e32 v130, s76, v157
	s_cselect_b32 s35, s21, s69
	s_cselect_b32 s34, s62, s68
	s_add_i32 s80, 0, 0x14000
	ds_read_b128 v[162:165], v130
	ds_read_b128 v[166:169], v130 offset:1024
	ds_read_b128 v[170:173], v130 offset:2048
	ds_read_b128 v[174:177], v130 offset:3072
	v_add_u32_e32 v130, s80, v157
	ds_read_b128 v[178:181], v130
	ds_read_b128 v[182:185], v130 offset:1024
	ds_read_b128 v[186:189], v130 offset:2048
	ds_read_b128 v[190:193], v130 offset:3072
	v_lshl_add_u64 v[130:131], s[30:31], 0, v[148:149]
	s_add_i32 m0, s54, 0xc000
	ds_read_b128 v[194:197], v161
	ds_read_b128 v[198:201], v161 offset:1024
	ds_read_b128 v[202:205], v161 offset:2048
	ds_read_b128 v[218:221], v161 offset:3072
	ds_read_b128 v[222:225], v161 offset:4096
	ds_read_b128 v[226:229], v161 offset:5120
	ds_read_b128 v[230:233], v161 offset:6144
	ds_read_b128 v[234:237], v161 offset:7168
	global_load_lds_dwordx4 v[130:131], off
	v_lshl_add_u64 v[130:131], s[30:31], 0, v[150:151]
	s_add_i32 m0, s54, 0xe000
	s_nop 0
	global_load_lds_dwordx4 v[130:131], off
	s_waitcnt vmcnt(8)
	s_waitcnt lgkmcnt(0)
	s_barrier
	s_setprio 1
	s_waitcnt lgkmcnt(0)
	v_mfma_f32_16x16x32_bf16 v[124:127], v[162:165], v[194:197], 0
	v_mfma_f32_16x16x32_bf16 v[120:123], v[170:173], v[194:197], 0
	v_mfma_f32_16x16x32_bf16 v[108:111], v[162:165], v[202:205], 0
	v_mfma_f32_16x16x32_bf16 v[104:107], v[170:173], v[202:205], 0
	v_mfma_f32_16x16x32_bf16 v[92:95], v[162:165], v[222:225], 0
	v_mfma_f32_16x16x32_bf16 v[88:91], v[170:173], v[222:225], 0
	v_mfma_f32_16x16x32_bf16 v[76:79], v[162:165], v[230:233], 0
	v_mfma_f32_16x16x32_bf16 v[72:75], v[170:173], v[230:233], 0
	v_mfma_f32_16x16x32_bf16 v[124:127], v[166:169], v[198:201], v[124:127]
	v_mfma_f32_16x16x32_bf16 v[120:123], v[174:177], v[198:201], v[120:123]
	v_mfma_f32_16x16x32_bf16 v[108:111], v[166:169], v[218:221], v[108:111]
	v_mfma_f32_16x16x32_bf16 v[104:107], v[174:177], v[218:221], v[104:107]
	v_mfma_f32_16x16x32_bf16 v[92:95], v[166:169], v[226:229], v[92:95]
	v_mfma_f32_16x16x32_bf16 v[88:91], v[174:177], v[226:229], v[88:91]
	v_mfma_f32_16x16x32_bf16 v[76:79], v[166:169], v[234:237], v[76:79]
	v_mfma_f32_16x16x32_bf16 v[72:75], v[174:177], v[234:237], v[72:75]
	s_setprio 0
	s_setprio 1
	v_mfma_f32_16x16x32_bf16 v[116:119], v[178:181], v[194:197], 0
	v_mfma_f32_16x16x32_bf16 v[112:115], v[186:189], v[194:197], 0
	v_mfma_f32_16x16x32_bf16 v[100:103], v[178:181], v[202:205], 0
	v_mfma_f32_16x16x32_bf16 v[96:99], v[186:189], v[202:205], 0
	v_mfma_f32_16x16x32_bf16 v[84:87], v[178:181], v[222:225], 0
	v_mfma_f32_16x16x32_bf16 v[80:83], v[186:189], v[222:225], 0
	v_mfma_f32_16x16x32_bf16 v[68:71], v[178:181], v[230:233], 0
	v_mfma_f32_16x16x32_bf16 v[64:67], v[186:189], v[230:233], 0
	v_mfma_f32_16x16x32_bf16 v[116:119], v[182:185], v[198:201], v[116:119]
	v_mfma_f32_16x16x32_bf16 v[112:115], v[190:193], v[198:201], v[112:115]
	v_mfma_f32_16x16x32_bf16 v[100:103], v[182:185], v[218:221], v[100:103]
	v_mfma_f32_16x16x32_bf16 v[96:99], v[190:193], v[218:221], v[96:99]
	v_mfma_f32_16x16x32_bf16 v[84:87], v[182:185], v[226:229], v[84:87]
	v_mfma_f32_16x16x32_bf16 v[80:83], v[190:193], v[226:229], v[80:83]
	v_mfma_f32_16x16x32_bf16 v[68:71], v[182:185], v[234:237], v[68:71]
	v_mfma_f32_16x16x32_bf16 v[64:67], v[190:193], v[234:237], v[64:67]
	s_setprio 0
	s_barrier
	s_add_i32 s76, s76, s48
	v_lshl_add_u64 v[130:131], s[34:35], 0, v[128:129]
	s_mov_b32 m0, s76
	ds_read_b128 v[194:197], v161 offset:16384
	ds_read_b128 v[198:201], v161 offset:17408
	ds_read_b128 v[202:205], v161 offset:18432
	ds_read_b128 v[218:221], v161 offset:19456
	ds_read_b128 v[222:225], v161 offset:20480
	ds_read_b128 v[226:229], v161 offset:21504
	ds_read_b128 v[230:233], v161 offset:22528
	ds_read_b128 v[234:237], v161 offset:23552
	global_load_lds_dwordx4 v[130:131], off
	s_add_i32 m0, s76, 0x2000
	s_add_u32 s76, s34, 0x80000
	v_lshl_add_u64 v[132:133], s[34:35], 0, v[142:143]
	s_addc_u32 s77, s35, 0
	s_add_i32 s80, s80, s48
	global_load_lds_dwordx4 v[132:133], off
	v_lshl_add_u64 v[154:155], s[76:77], 0, v[128:129]
	s_mov_b32 m0, s80
	v_lshl_add_u64 v[206:207], s[42:43], 0, v[144:145]
	global_load_lds_dwordx4 v[154:155], off
	v_lshl_add_u64 v[154:155], s[76:77], 0, v[142:143]
	s_add_i32 m0, s80, 0x2000
	s_nop 0
	global_load_lds_dwordx4 v[154:155], off
	v_lshl_add_u64 v[154:155], s[42:43], 0, v[146:147]
	s_mov_b32 m0, s54
	s_nop 0
	global_load_lds_dwordx4 v[154:155], off
	s_mov_b32 m0, s55
	s_nop 0
	global_load_lds_dwordx4 v[206:207], off
	s_waitcnt vmcnt(8)
	s_waitcnt lgkmcnt(0)
	s_barrier
; #define PG8_STAGE(bufoff, gbase, voff) do { _Pragma("unroll") for (int _i = 0; _i < 2; ++_i) \
;         __builtin_amdgcn_global_load_lds((const unsigned*)((const char*)(gbase) + (voff)[_i]), (PG8_LAS unsigned*)(lds + (bufoff) + ldsw + _i * 8192), 16, 0, 0); } while (0)
; #define PG8_LDA(dst, b, h) do { _Pragma("unroll") for (int m = 0; m < 4; ++m) _Pragma("unroll") for (int k = 0; k < 2; ++k) dst[m][k] = *(const PG8_LAS bf16x8*)(lds + PG8_SA(b, h) + aoff + m * 2048 + k * 1024); } while (0)
; #define PG8_LDB(dst, b, h) do { _Pragma("unroll") for (int n = 0; n < 2; ++n) _Pragma("unroll") for (int k = 0; k < 2; ++k) dst[n][k] = *(const PG8_LAS bf16x8*)(lds + PG8_SB(b, h) + boff + n * 2048 + k * 1024); } while (0)
; #define PG8_MMA(ai, bj, At, Bt) do { __builtin_amdgcn_s_setprio(1); _Pragma("unroll") for (int m = 0; m < 4; ++m) _Pragma("unroll") for (int n = 0; n < 2; ++n) _Pragma("unroll") for (int k = 0; k < 2; ++k) \
;         acc[ai][bj][m][n] = __builtin_amdgcn_mfma_f32_16x16x32_bf16(Bt[n][k], At[m][k], acc[ai][bj][m][n], 0, 0, 0); __builtin_amdgcn_s_setprio(0); } while (0)
; #define PG8_WAIT_V(n) asm volatile("s_waitcnt vmcnt(" #n ")" ::: "memory")
; #define PG8_WAIT_L(n) asm volatile("s_waitcnt lgkmcnt(" #n ")" ::: "memory")
; #define PG8_BAR __builtin_amdgcn_s_barrier()
; #define PG8_SCHED __builtin_amdgcn_sched_barrier(0)
; template <class Epi, class Sched, bool ALIGN_EPI = false, bool SP2 = false>
; __device__ __forceinline__ void gemm_phase(PG8_LAS unsigned char* lds, const Gemm g, const Sched& S, const Epi& E) {
;     ...
;             PG8_WAIT_V(8); PG8_WAIT_L(0); PG8_BAR; PG8_MMA(1, 0, At, B0); PG8_MMA(1, 1, At, B1); PG8_BAR; PG8_SCHED;
;             PG8_LDB(B0, 1, 0); PG8_LDB(B1, 1, 1); PG8_SCHED; PG8_LDA(At, 1, 0); PG8_STAGE(PG8_SA(0, 1), a2 + hstep, voffA);
;             PG8_WAIT_V(8); PG8_WAIT_L(0); PG8_BAR; PG8_MMA(0, 0, At, B0); PG8_MMA(0, 1, At, B1); PG8_BAR; PG8_SCHED;
	s_setprio 1
	s_waitcnt lgkmcnt(0)
	v_mfma_f32_16x16x32_bf16 v[60:63], v[162:165], v[194:197], 0
	v_mfma_f32_16x16x32_bf16 v[56:59], v[170:173], v[194:197], 0
	v_mfma_f32_16x16x32_bf16 v[44:47], v[162:165], v[202:205], 0
	v_mfma_f32_16x16x32_bf16 v[40:43], v[170:173], v[202:205], 0
	v_mfma_f32_16x16x32_bf16 v[28:31], v[162:165], v[222:225], 0
	v_mfma_f32_16x16x32_bf16 v[24:27], v[170:173], v[222:225], 0
	v_mfma_f32_16x16x32_bf16 v[12:15], v[162:165], v[230:233], 0
	v_mfma_f32_16x16x32_bf16 v[8:11], v[170:173], v[230:233], 0
	v_mfma_f32_16x16x32_bf16 v[60:63], v[166:169], v[198:201], v[60:63]
	v_mfma_f32_16x16x32_bf16 v[56:59], v[174:177], v[198:201], v[56:59]
	v_mfma_f32_16x16x32_bf16 v[44:47], v[166:169], v[218:221], v[44:47]
	v_mfma_f32_16x16x32_bf16 v[40:43], v[174:177], v[218:221], v[40:43]
	v_mfma_f32_16x16x32_bf16 v[28:31], v[166:169], v[226:229], v[28:31]
	v_mfma_f32_16x16x32_bf16 v[24:27], v[174:177], v[226:229], v[24:27]
	v_mfma_f32_16x16x32_bf16 v[12:15], v[166:169], v[234:237], v[12:15]
	v_mfma_f32_16x16x32_bf16 v[8:11], v[174:177], v[234:237], v[8:11]
	s_setprio 0
	s_setprio 1
	v_mfma_f32_16x16x32_bf16 v[52:55], v[178:181], v[194:197], 0
	v_mfma_f32_16x16x32_bf16 v[48:51], v[186:189], v[194:197], 0
	v_mfma_f32_16x16x32_bf16 v[36:39], v[178:181], v[202:205], 0
	v_mfma_f32_16x16x32_bf16 v[32:35], v[186:189], v[202:205], 0
	v_mfma_f32_16x16x32_bf16 v[20:23], v[178:181], v[222:225], 0
	v_mfma_f32_16x16x32_bf16 v[16:19], v[186:189], v[222:225], 0
	v_mfma_f32_16x16x32_bf16 v[4:7], v[178:181], v[230:233], 0
	v_mfma_f32_16x16x32_bf16 v[0:3], v[186:189], v[230:233], 0
	v_mfma_f32_16x16x32_bf16 v[52:55], v[182:185], v[198:201], v[52:55]
	v_mfma_f32_16x16x32_bf16 v[48:51], v[190:193], v[198:201], v[48:51]
	v_mfma_f32_16x16x32_bf16 v[36:39], v[182:185], v[218:221], v[36:39]
	v_mfma_f32_16x16x32_bf16 v[32:35], v[190:193], v[218:221], v[32:35]
	v_mfma_f32_16x16x32_bf16 v[20:23], v[182:185], v[226:229], v[20:23]
	v_mfma_f32_16x16x32_bf16 v[16:19], v[190:193], v[226:229], v[16:19]
	v_mfma_f32_16x16x32_bf16 v[4:7], v[182:185], v[234:237], v[4:7]
	v_mfma_f32_16x16x32_bf16 v[0:3], v[190:193], v[234:237], v[0:3]
	s_setprio 0
	s_barrier
	s_add_i32 s76, 0, 0x18000
	v_add_u32_e32 v134, s76, v157
	s_add_i32 s77, 0, 0x1c000
	ds_read_b128 v[162:165], v134
	ds_read_b128 v[166:169], v134 offset:1024
	ds_read_b128 v[170:173], v134 offset:2048
	ds_read_b128 v[174:177], v134 offset:3072
	v_add_u32_e32 v134, s77, v157
	ds_read_b128 v[178:181], v134
	ds_read_b128 v[182:185], v134 offset:1024
	ds_read_b128 v[186:189], v134 offset:2048
	ds_read_b128 v[190:193], v134 offset:3072
	s_add_u32 s42, s42, 0x80000
	s_addc_u32 s43, s43, 0
	s_mov_b32 m0, s56
	v_lshl_add_u64 v[238:239], s[42:43], 0, v[146:147]
	ds_read_b128 v[194:197], v161 offset:32768
	ds_read_b128 v[198:201], v161 offset:33792
	ds_read_b128 v[202:205], v161 offset:34816
	ds_read_b128 v[218:221], v161 offset:35840
	ds_read_b128 v[222:225], v161 offset:36864
	ds_read_b128 v[226:229], v161 offset:37888
	ds_read_b128 v[230:233], v161 offset:38912
	ds_read_b128 v[234:237], v161 offset:39936
	global_load_lds_dwordx4 v[238:239], off
	v_lshl_add_u64 v[238:239], s[42:43], 0, v[144:145]
	s_mov_b32 m0, s57
	s_nop 0
	global_load_lds_dwordx4 v[238:239], off
	s_waitcnt vmcnt(8)
	s_waitcnt lgkmcnt(0)
	s_barrier
	s_setprio 1
	s_waitcnt lgkmcnt(0)
	v_mfma_f32_16x16x32_bf16 v[124:127], v[162:165], v[194:197], v[124:127]
	v_mfma_f32_16x16x32_bf16 v[120:123], v[170:173], v[194:197], v[120:123]
	v_mfma_f32_16x16x32_bf16 v[108:111], v[162:165], v[202:205], v[108:111]
	v_mfma_f32_16x16x32_bf16 v[104:107], v[170:173], v[202:205], v[104:107]
	v_mfma_f32_16x16x32_bf16 v[92:95], v[162:165], v[222:225], v[92:95]
	v_mfma_f32_16x16x32_bf16 v[88:91], v[170:173], v[222:225], v[88:91]
	v_mfma_f32_16x16x32_bf16 v[76:79], v[162:165], v[230:233], v[76:79]
	v_mfma_f32_16x16x32_bf16 v[72:75], v[170:173], v[230:233], v[72:75]
	v_mfma_f32_16x16x32_bf16 v[124:127], v[166:169], v[198:201], v[124:127]
	v_mfma_f32_16x16x32_bf16 v[120:123], v[174:177], v[198:201], v[120:123]
	v_mfma_f32_16x16x32_bf16 v[108:111], v[166:169], v[218:221], v[108:111]
	v_mfma_f32_16x16x32_bf16 v[104:107], v[174:177], v[218:221], v[104:107]
	v_mfma_f32_16x16x32_bf16 v[92:95], v[166:169], v[226:229], v[92:95]
	v_mfma_f32_16x16x32_bf16 v[88:91], v[174:177], v[226:229], v[88:91]
	v_mfma_f32_16x16x32_bf16 v[76:79], v[166:169], v[234:237], v[76:79]
	v_mfma_f32_16x16x32_bf16 v[72:75], v[174:177], v[234:237], v[72:75]
	s_setprio 0
	s_setprio 1
	v_mfma_f32_16x16x32_bf16 v[116:119], v[178:181], v[194:197], v[116:119]
	v_mfma_f32_16x16x32_bf16 v[112:115], v[186:189], v[194:197], v[112:115]
	v_mfma_f32_16x16x32_bf16 v[100:103], v[178:181], v[202:205], v[100:103]
	v_mfma_f32_16x16x32_bf16 v[96:99], v[186:189], v[202:205], v[96:99]
	v_mfma_f32_16x16x32_bf16 v[84:87], v[178:181], v[222:225], v[84:87]
	v_mfma_f32_16x16x32_bf16 v[80:83], v[186:189], v[222:225], v[80:83]
	v_mfma_f32_16x16x32_bf16 v[68:71], v[178:181], v[230:233], v[68:71]
	v_mfma_f32_16x16x32_bf16 v[64:67], v[186:189], v[230:233], v[64:67]
	v_mfma_f32_16x16x32_bf16 v[116:119], v[182:185], v[198:201], v[116:119]
	v_mfma_f32_16x16x32_bf16 v[112:115], v[190:193], v[198:201], v[112:115]
	v_mfma_f32_16x16x32_bf16 v[100:103], v[182:185], v[218:221], v[100:103]
	v_mfma_f32_16x16x32_bf16 v[96:99], v[190:193], v[218:221], v[96:99]
	v_mfma_f32_16x16x32_bf16 v[84:87], v[182:185], v[226:229], v[84:87]
	v_mfma_f32_16x16x32_bf16 v[80:83], v[190:193], v[226:229], v[80:83]
	v_mfma_f32_16x16x32_bf16 v[68:71], v[182:185], v[234:237], v[68:71]
	v_mfma_f32_16x16x32_bf16 v[64:67], v[190:193], v[234:237], v[64:67]
	s_setprio 0
	s_barrier
; #define PG8_STAGE(bufoff, gbase, voff) do { _Pragma("unroll") for (int _i = 0; _i < 2; ++_i) \
;         __builtin_amdgcn_global_load_lds((const unsigned*)((const char*)(gbase) + (voff)[_i]), (PG8_LAS unsigned*)(lds + (bufoff) + ldsw + _i * 8192), 16, 0, 0); } while (0)
; #define PG8_LDA(dst, b, h) do { _Pragma("unroll") for (int m = 0; m < 4; ++m) _Pragma("unroll") for (int k = 0; k < 2; ++k) dst[m][k] = *(const PG8_LAS bf16x8*)(lds + PG8_SA(b, h) + aoff + m * 2048 + k * 1024); } while (0)
; #define PG8_MMA(ai, bj, At, Bt) do { __builtin_amdgcn_s_setprio(1); _Pragma("unroll") for (int m = 0; m < 4; ++m) _Pragma("unroll") for (int n = 0; n < 2; ++n) _Pragma("unroll") for (int k = 0; k < 2; ++k) \
;         acc[ai][bj][m][n] = __builtin_amdgcn_mfma_f32_16x16x32_bf16(Bt[n][k], At[m][k], acc[ai][bj][m][n], 0, 0, 0); __builtin_amdgcn_s_setprio(0); } while (0)
; #define PG8_WAIT_V(n) asm volatile("s_waitcnt vmcnt(" #n ")" ::: "memory")
; #define PG8_WAIT_L(n) asm volatile("s_waitcnt lgkmcnt(" #n ")" ::: "memory")
; #define PG8_BAR __builtin_amdgcn_s_barrier()
; #define PG8_SCHED __builtin_amdgcn_sched_barrier(0)
; template <class Epi, class Sched, bool ALIGN_EPI = false, bool SP2 = false>
; __device__ __forceinline__ void gemm_phase(PG8_LAS unsigned char* lds, const Gemm g, const Sched& S, const Epi& E) {
;     ...
;         for (int t = 0; t < nt; t += 2) {
;     ...
;             PG8_LDA(At, 1, 1); PG8_STAGE(PG8_SB(1, 0), b3, voffB); PG8_STAGE(PG8_SB(1, 1), b3 + hstep, voffB); PG8_STAGE(PG8_SA(1, 0), a3, voffA);
;             PG8_WAIT_V(8); PG8_WAIT_L(0); PG8_BAR; PG8_MMA(1, 0, At, B0); PG8_MMA(1, 1, At, B1); PG8_BAR; PG8_SCHED;
	s_add_i32 s42, s76, s48
	v_lshl_add_u64 v[130:131], v[130:131], 0, s[78:79]
	s_mov_b32 m0, s42
	ds_read_b128 v[194:197], v161 offset:49152
	ds_read_b128 v[198:201], v161 offset:50176
	ds_read_b128 v[202:205], v161 offset:51200
	ds_read_b128 v[218:221], v161 offset:52224
	ds_read_b128 v[222:225], v161 offset:53248
	ds_read_b128 v[226:229], v161 offset:54272
	ds_read_b128 v[230:233], v161 offset:55296
	ds_read_b128 v[234:237], v161 offset:56320
	global_load_lds_dwordx4 v[130:131], off
	s_add_i32 m0, s42, 0x2000
	s_add_u32 s34, s34, 0x80080
	v_lshl_add_u64 v[130:131], v[132:133], 0, s[78:79]
	s_addc_u32 s35, s35, 0
	s_add_i32 s42, s77, s48
	global_load_lds_dwordx4 v[130:131], off
	v_lshl_add_u64 v[130:131], s[34:35], 0, v[128:129]
	s_mov_b32 m0, s42
	s_nop 0
	global_load_lds_dwordx4 v[130:131], off
	v_lshl_add_u64 v[130:131], s[34:35], 0, v[142:143]
	s_add_i32 m0, s42, 0x2000
	s_nop 0
	global_load_lds_dwordx4 v[130:131], off
	v_lshl_add_u64 v[130:131], v[154:155], 0, s[78:79]
	s_mov_b32 m0, s58
	s_nop 0
	global_load_lds_dwordx4 v[130:131], off
	v_lshl_add_u64 v[130:131], v[206:207], 0, s[78:79]
	s_mov_b32 m0, s59
	s_nop 0
	global_load_lds_dwordx4 v[130:131], off
	s_waitcnt vmcnt(8)
	s_waitcnt lgkmcnt(0)
	s_barrier
	s_setprio 1
	s_waitcnt lgkmcnt(0)
	v_mfma_f32_16x16x32_bf16 v[60:63], v[162:165], v[194:197], v[60:63]
	v_mfma_f32_16x16x32_bf16 v[56:59], v[170:173], v[194:197], v[56:59]
	v_mfma_f32_16x16x32_bf16 v[44:47], v[162:165], v[202:205], v[44:47]
	v_mfma_f32_16x16x32_bf16 v[40:43], v[170:173], v[202:205], v[40:43]
	v_mfma_f32_16x16x32_bf16 v[28:31], v[162:165], v[222:225], v[28:31]
	v_mfma_f32_16x16x32_bf16 v[24:27], v[170:173], v[222:225], v[24:27]
	v_mfma_f32_16x16x32_bf16 v[12:15], v[162:165], v[230:233], v[12:15]
	v_mfma_f32_16x16x32_bf16 v[8:11], v[170:173], v[230:233], v[8:11]
	v_mfma_f32_16x16x32_bf16 v[60:63], v[166:169], v[198:201], v[60:63]
	v_mfma_f32_16x16x32_bf16 v[56:59], v[174:177], v[198:201], v[56:59]
	v_mfma_f32_16x16x32_bf16 v[44:47], v[166:169], v[218:221], v[44:47]
	v_mfma_f32_16x16x32_bf16 v[40:43], v[174:177], v[218:221], v[40:43]
	v_mfma_f32_16x16x32_bf16 v[28:31], v[166:169], v[226:229], v[28:31]
	v_mfma_f32_16x16x32_bf16 v[24:27], v[174:177], v[226:229], v[24:27]
	v_mfma_f32_16x16x32_bf16 v[12:15], v[166:169], v[234:237], v[12:15]
	v_mfma_f32_16x16x32_bf16 v[8:11], v[174:177], v[234:237], v[8:11]
	s_setprio 0
	s_setprio 1
	v_mfma_f32_16x16x32_bf16 v[52:55], v[178:181], v[194:197], v[52:55]
	v_mfma_f32_16x16x32_bf16 v[48:51], v[186:189], v[194:197], v[48:51]
	v_mfma_f32_16x16x32_bf16 v[36:39], v[178:181], v[202:205], v[36:39]
	v_mfma_f32_16x16x32_bf16 v[32:35], v[186:189], v[202:205], v[32:35]
	v_mfma_f32_16x16x32_bf16 v[20:23], v[178:181], v[222:225], v[20:23]
	v_mfma_f32_16x16x32_bf16 v[16:19], v[186:189], v[222:225], v[16:19]
	v_mfma_f32_16x16x32_bf16 v[4:7], v[178:181], v[230:233], v[4:7]
	v_mfma_f32_16x16x32_bf16 v[0:3], v[186:189], v[230:233], v[0:3]
	v_mfma_f32_16x16x32_bf16 v[52:55], v[182:185], v[198:201], v[52:55]
	v_mfma_f32_16x16x32_bf16 v[48:51], v[190:193], v[198:201], v[48:51]
	v_mfma_f32_16x16x32_bf16 v[36:39], v[182:185], v[218:221], v[36:39]
	v_mfma_f32_16x16x32_bf16 v[32:35], v[190:193], v[218:221], v[32:35]
	v_mfma_f32_16x16x32_bf16 v[20:23], v[182:185], v[226:229], v[20:23]
	v_mfma_f32_16x16x32_bf16 v[16:19], v[190:193], v[226:229], v[16:19]
	v_mfma_f32_16x16x32_bf16 v[4:7], v[182:185], v[234:237], v[4:7]
	v_mfma_f32_16x16x32_bf16 v[0:3], v[190:193], v[234:237], v[0:3]
	s_setprio 0
	s_barrier
	s_add_i32 s74, s74, 2
	s_add_u32 s30, s30, 0x100
	s_addc_u32 s31, s31, 0
	s_add_u32 s68, s68, 0x100
	s_addc_u32 s69, s69, 0
	s_cmp_gt_u32 s74, 29
